# same as previous but bf16 weight/PB stores of the P2 conversions left cacheable (only their f32 source loads are non-temporal)
# speedup vs baseline: 1.0478x; 1.0087x over previous
; #define LAS __attribute__((address_space(3)))
; template <bool F8 = false>
; __device__ __forceinline__ void p0_transpose_item(const float* W, int K, int N, bf16_t* WT, int k0, int n0, int drow0, const float* gs, LAS float* scr, int lane) {
;     float wv[32];
; #pragma unroll
;     for (int i = 0; i < 32; ++i) wv[i] = W[(size_t)(k0 + 2 * i + (lane >> 5)) * N + n0 + (lane & 31)];
;     if (gs) {
; #pragma unroll
;         for (int i = 0; i < 32; ++i) wv[i] *= gs[k0 + 2 * i + (lane >> 5)]; }
; #pragma unroll
;     for (int i = 0; i < 32; ++i) scr[(2 * i + (lane >> 5)) * 33 + (lane & 31)] = wv[i];
;     asm volatile("s_waitcnt lgkmcnt(0)" ::: "memory");
; template <int PART>
; __device__ __forceinline__ void phase0(const Ptrs& P, LAS float* scr, int gw, int NGW, int lane) {
;     ...
;         { const int nblk = DM / 32; p0_transpose_item(P.w_ple, PLE, DM, (bf16_t*)(ws + WS_WPLE), 64 * (r / nblk), 32 * (r % nblk), 32 * (r % nblk), nullptr, scr, lane); }
.LBB0_413:
	s_cmp_gt_i32 s24, -1
	s_mov_b64 s[0:1], -1
	s_cbranch_scc0 .LBB0_443
	s_cmpk_gt_u32 s24, 0x1ff
	s_cbranch_scc0 .LBB0_440
	s_cmpk_gt_u32 s24, 0x3ff
	s_cbranch_scc0 .LBB0_437
	s_cmpk_gt_u32 s24, 0x5ff
	s_cbranch_scc0 .LBB0_434
	s_cmpk_gt_u32 s24, 0x7ff
	s_cbranch_scc0 .LBB0_429
	s_cmpk_gt_u32 s24, 0xfff
	s_cbranch_scc0 .LBB0_424
	s_and_b32 s2, s8, 0x3e0
	s_cmpk_gt_u32 s24, 0x17ff
	v_add_u32_e32 v40, s2, v75
	v_add_u32_e32 v38, s2, v77
	v_add_u32_e32 v36, s2, v78
	v_add_u32_e32 v34, s2, v79
	s_cbranch_scc0 .LBB0_421
	s_and_b32 s0, s9, 0x7fffffc0
	v_add_u32_e32 v42, s0, v70
	s_lshl_b32 s68, s2, 2
	v_ashrrev_i32_e32 v43, 31, v42
	v_lshl_add_u64 v[44:45], v[18:19], 0, s[68:69]
	v_lshlrev_b64 v[42:43], 12, v[42:43]
	v_lshl_add_u64 v[42:43], v[44:45], 0, v[42:43]
	v_add_co_u32_e32 v44, vcc, 0x2000, v42
	global_load_dword v35, v[42:43], off nt
	s_nop 0
	v_addc_co_u32_e32 v45, vcc, 0, v43, vcc
	global_load_dword v37, v[44:45], off nt
	v_add_co_u32_e32 v44, vcc, 0x4000, v42
	s_lshl_b32 s68, s0, 1
	s_nop 0
	v_addc_co_u32_e32 v45, vcc, 0, v43, vcc
	global_load_dword v39, v[44:45], off nt
	v_add_co_u32_e32 v44, vcc, 0x6000, v42
	s_mov_b64 s[0:1], 0
	s_nop 0
	v_addc_co_u32_e32 v45, vcc, 0, v43, vcc
	global_load_dword v41, v[44:45], off nt
	v_add_co_u32_e32 v44, vcc, 0x8000, v42
	s_nop 1
	v_addc_co_u32_e32 v45, vcc, 0, v43, vcc
	global_load_dword v46, v[44:45], off nt
	v_add_co_u32_e32 v44, vcc, 0xa000, v42
	s_nop 1
	v_addc_co_u32_e32 v45, vcc, 0, v43, vcc
	global_load_dword v47, v[44:45], off nt
	v_add_co_u32_e32 v44, vcc, 0xc000, v42
	s_nop 1
	v_addc_co_u32_e32 v45, vcc, 0, v43, vcc
	global_load_dword v48, v[44:45], off nt
	v_add_co_u32_e32 v44, vcc, 0xe000, v42
	s_nop 1
	v_addc_co_u32_e32 v45, vcc, 0, v43, vcc
	global_load_dword v49, v[44:45], off nt
	v_add_co_u32_e32 v44, vcc, 0x10000, v42
	s_nop 1
	v_addc_co_u32_e32 v45, vcc, 0, v43, vcc
	global_load_dword v50, v[44:45], off nt
	v_add_co_u32_e32 v44, vcc, 0x12000, v42
	s_nop 1
	v_addc_co_u32_e32 v45, vcc, 0, v43, vcc
	global_load_dword v51, v[44:45], off nt
	v_add_co_u32_e32 v44, vcc, 0x14000, v42
	s_nop 1
	v_addc_co_u32_e32 v45, vcc, 0, v43, vcc
	global_load_dword v52, v[44:45], off nt
	v_add_co_u32_e32 v44, vcc, 0x16000, v42
	s_nop 1
	v_addc_co_u32_e32 v45, vcc, 0, v43, vcc
	global_load_dword v53, v[44:45], off nt
	v_add_co_u32_e32 v44, vcc, 0x18000, v42
	s_nop 1
	v_addc_co_u32_e32 v45, vcc, 0, v43, vcc
	global_load_dword v54, v[44:45], off nt
	v_add_co_u32_e32 v44, vcc, 0x1a000, v42
	s_nop 1
	v_addc_co_u32_e32 v45, vcc, 0, v43, vcc
	global_load_dword v55, v[44:45], off nt
	v_add_co_u32_e32 v44, vcc, 0x1c000, v42
	s_nop 1
	v_addc_co_u32_e32 v45, vcc, 0, v43, vcc
	global_load_dword v56, v[44:45], off nt
	v_add_co_u32_e32 v44, vcc, 0x1e000, v42
	s_nop 1
	v_addc_co_u32_e32 v45, vcc, 0, v43, vcc
	global_load_dword v57, v[44:45], off nt
	v_add_co_u32_e32 v44, vcc, 0x20000, v42
	s_nop 1
	v_addc_co_u32_e32 v45, vcc, 0, v43, vcc
	global_load_dword v58, v[44:45], off nt
	v_add_co_u32_e32 v44, vcc, 0x22000, v42
	s_nop 1
	v_addc_co_u32_e32 v45, vcc, 0, v43, vcc
	global_load_dword v59, v[44:45], off nt
	v_add_co_u32_e32 v44, vcc, 0x24000, v42
	s_nop 1
	v_addc_co_u32_e32 v45, vcc, 0, v43, vcc
	global_load_dword v60, v[44:45], off nt
	v_add_co_u32_e32 v44, vcc, 0x26000, v42
	s_nop 1
	v_addc_co_u32_e32 v45, vcc, 0, v43, vcc
	global_load_dword v61, v[44:45], off nt
	v_add_co_u32_e32 v44, vcc, 0x28000, v42
	s_nop 1
	v_addc_co_u32_e32 v45, vcc, 0, v43, vcc
	global_load_dword v62, v[44:45], off nt
	v_add_co_u32_e32 v44, vcc, 0x2a000, v42
	s_nop 1
	v_addc_co_u32_e32 v45, vcc, 0, v43, vcc
	global_load_dword v63, v[44:45], off nt
	v_add_co_u32_e32 v44, vcc, 0x2c000, v42
	s_nop 1
	v_addc_co_u32_e32 v45, vcc, 0, v43, vcc
	global_load_dword v64, v[44:45], off nt
	v_add_co_u32_e32 v44, vcc, 0x2e000, v42
	s_nop 1
	v_addc_co_u32_e32 v45, vcc, 0, v43, vcc
	global_load_dword v65, v[44:45], off nt
	v_add_co_u32_e32 v44, vcc, 0x30000, v42
	s_nop 1
	v_addc_co_u32_e32 v45, vcc, 0, v43, vcc
	global_load_dword v66, v[44:45], off nt
	v_add_co_u32_e32 v44, vcc, 0x32000, v42
	s_nop 1
	v_addc_co_u32_e32 v45, vcc, 0, v43, vcc
	global_load_dword v67, v[44:45], off nt
	v_add_co_u32_e32 v44, vcc, 0x34000, v42
	s_nop 1
	v_addc_co_u32_e32 v45, vcc, 0, v43, vcc
	global_load_dword v68, v[44:45], off nt
	v_add_co_u32_e32 v44, vcc, 0x36000, v42
	s_nop 1
	v_addc_co_u32_e32 v45, vcc, 0, v43, vcc
	global_load_dword v69, v[44:45], off nt
	v_add_co_u32_e32 v44, vcc, 0x38000, v42
	s_nop 1
	v_addc_co_u32_e32 v45, vcc, 0, v43, vcc
	global_load_dword v86, v[44:45], off nt
	v_add_co_u32_e32 v44, vcc, 0x3a000, v42
	s_nop 1
	v_addc_co_u32_e32 v45, vcc, 0, v43, vcc
	global_load_dword v87, v[44:45], off nt
	v_add_co_u32_e32 v44, vcc, 0x3c000, v42
	s_nop 1
	v_addc_co_u32_e32 v45, vcc, 0, v43, vcc
	v_add_co_u32_e32 v42, vcc, 0x3e000, v42
	global_load_dword v44, v[44:45], off nt
	s_nop 0
	v_addc_co_u32_e32 v43, vcc, 0, v43, vcc
	global_load_dword v42, v[42:43], off nt
	s_waitcnt vmcnt(0)
	ds_write2_b32 v71, v35, v37 offset1:66
	ds_write2_b32 v71, v39, v41 offset0:132 offset1:198
	ds_write2_b32 v72, v46, v47 offset0:8 offset1:74
	ds_write2_b32 v72, v48, v49 offset0:140 offset1:206
	ds_write2_b32 v80, v50, v51 offset0:16 offset1:82
	ds_write2_b32 v80, v52, v53 offset0:148 offset1:214
	ds_write2_b32 v82, v54, v55 offset0:24 offset1:90
	ds_write2_b32 v82, v56, v57 offset0:156 offset1:222
	ds_write2_b32 v83, v58, v59 offset0:32 offset1:98
	ds_write2_b32 v83, v60, v61 offset0:164 offset1:230
	ds_write2_b32 v84, v62, v63 offset0:40 offset1:106
	ds_write2_b32 v84, v64, v65 offset0:172 offset1:238
	ds_write2_b32 v85, v66, v67 offset0:48 offset1:114
	ds_write2_b32 v85, v68, v69 offset0:180 offset1:246
	v_add_u32_e32 v35, 0x1c00, v71
	ds_write2_b32 v35, v86, v87 offset0:56 offset1:122
	ds_write2_b32 v35, v44, v42 offset0:188 offset1:254
	s_waitcnt lgkmcnt(0)
; #define LAS __attribute__((address_space(3)))
; __device__ __forceinline__ unsigned cvt_pk(float lo, float hi) { f32x2_t v = {lo, hi}; bf16x2_t b = __builtin_convertvector(v, bf16x2_t); return __builtin_bit_cast(unsigned, b); }
; __device__ __forceinline__ unsigned pk_fp8x4(float a, float b, float c, float d) { int w = 0; w = __builtin_amdgcn_cvt_pk_fp8_f32(a, b, w, false); w = __builtin_amdgcn_cvt_pk_fp8_f32(c, d, w, true); return (unsigned)w; }
; template <bool F8 = false>
; __device__ __forceinline__ void p0_transpose_item(const float* W, int K, int N, bf16_t* WT, int k0, int n0, int drow0, const float* gs, LAS float* scr, int lane) {
;     ...
;     const int c = lane & 7;
; #pragma unroll
;     for (int j = 0; j < 4; ++j) { const int n = (lane >> 3) + 8 * j; const LAS float* s = scr + (8 * c) * 33 + n;
;         if (F8) { u32x2 o8; o8.x = pk_fp8x4(32.f * s[0 * 33], 32.f * s[1 * 33], 32.f * s[2 * 33], 32.f * s[3 * 33]); o8.y = pk_fp8x4(32.f * s[4 * 33], 32.f * s[5 * 33], 32.f * s[6 * 33], 32.f * s[7 * 33]);
;             *(u32x2*)((unsigned char*)WT + (size_t)(drow0 + n) * K + k0 + 8 * c) = o8; }
;         else { u32x4 o; o.x = cvt_pk(s[0 * 33], s[1 * 33]); o.y = cvt_pk(s[2 * 33], s[3 * 33]); o.z = cvt_pk(s[4 * 33], s[5 * 33]); o.w = cvt_pk(s[6 * 33], s[7 * 33]);
;             *(u32x4*)(WT + (size_t)(drow0 + n) * K + k0 + 8 * c) = o; } }
; template <int PART>
; __device__ __forceinline__ void phase0(const Ptrs& P, LAS float* scr, int gw, int NGW, int lane) {
;     ...
;         if (r < I_DN) { const int nblk = DM / 32; p0_transpose_item(P.w_dn, FF, DM, (bf16_t*)(ws + WS_WDN), 64 * (r / nblk), 32 * (r % nblk), 32 * (r % nblk), nullptr, scr, lane); continue; } r -= I_DN;
	ds_read2_b32 v[48:49], v76 offset0:33 offset1:41
	ds_read2_b32 v[50:51], v76 offset1:8
	ds_read2_b32 v[52:53], v76 offset0:66 offset1:74
	ds_read2_b32 v[54:55], v76 offset0:99 offset1:107
	ds_read2_b32 v[56:57], v76 offset0:132 offset1:140
	ds_read2_b32 v[58:59], v76 offset0:165 offset1:173
	ds_read2_b32 v[60:61], v76 offset0:198 offset1:206
	ds_read2_b32 v[62:63], v76 offset0:231 offset1:239
	v_ashrrev_i32_e32 v41, 31, v40
	v_lshl_add_u64 v[46:47], v[0:1], 0, s[68:69]
	v_lshlrev_b64 v[64:65], 9, v[40:41]
	s_waitcnt lgkmcnt(6)
	v_cvt_pk_bf16_f32 v42, v50, v48
	s_waitcnt lgkmcnt(4)
	v_cvt_pk_bf16_f32 v43, v52, v54
	s_waitcnt lgkmcnt(2)
	v_cvt_pk_bf16_f32 v44, v56, v58
	s_waitcnt lgkmcnt(0)
	v_cvt_pk_bf16_f32 v45, v60, v62
	v_lshl_add_u64 v[64:65], v[46:47], 0, v[64:65]
	v_ashrrev_i32_e32 v39, 31, v38
	global_store_dwordx4 v[64:65], v[42:45], off
	v_ashrrev_i32_e32 v37, 31, v36
	v_lshlrev_b64 v[64:65], 9, v[36:37]
	v_cvt_pk_bf16_f32 v42, v51, v49
	v_lshlrev_b64 v[48:49], 9, v[38:39]
	v_cvt_pk_bf16_f32 v43, v53, v55
	v_cvt_pk_bf16_f32 v44, v57, v59
	v_cvt_pk_bf16_f32 v45, v61, v63
	v_lshl_add_u64 v[48:49], v[46:47], 0, v[48:49]
	global_store_dwordx4 v[48:49], v[42:45], off
	ds_read2_b32 v[48:49], v76 offset0:16 offset1:24
	ds_read2_b32 v[50:51], v76 offset0:49 offset1:57
	ds_read2_b32 v[52:53], v76 offset0:82 offset1:90
	ds_read2_b32 v[54:55], v76 offset0:115 offset1:123
	ds_read2_b32 v[56:57], v76 offset0:148 offset1:156
	ds_read2_b32 v[58:59], v76 offset0:181 offset1:189
	ds_read2_b32 v[60:61], v76 offset0:214 offset1:222
	ds_read2_b32 v[62:63], v76 offset0:247 offset1:255
	v_lshl_add_u64 v[64:65], v[46:47], 0, v[64:65]
	s_waitcnt lgkmcnt(6)
	v_cvt_pk_bf16_f32 v42, v48, v50
	s_waitcnt lgkmcnt(4)
	v_cvt_pk_bf16_f32 v43, v52, v54
	s_waitcnt lgkmcnt(2)
	v_cvt_pk_bf16_f32 v44, v56, v58
	s_waitcnt lgkmcnt(0)
	v_cvt_pk_bf16_f32 v45, v60, v62
	v_ashrrev_i32_e32 v35, 31, v34
	global_store_dwordx4 v[64:65], v[42:45], off
	s_nop 1
	v_cvt_pk_bf16_f32 v42, v49, v51
	v_lshlrev_b64 v[48:49], 9, v[34:35]
	v_cvt_pk_bf16_f32 v43, v53, v55
	v_cvt_pk_bf16_f32 v44, v57, v59
	v_cvt_pk_bf16_f32 v45, v61, v63
	v_lshl_add_u64 v[46:47], v[46:47], 0, v[48:49]
	global_store_dwordx4 v[46:47], v[42:45], off
	s_waitcnt lgkmcnt(0)
.LBB0_421:
	s_andn2_b64 vcc, exec, s[0:1]
	s_cbranch_vccnz .LBB0_423
	s_add_i32 s0, s9, 0x1000
	s_and_b32 s0, s0, 0x7fffffc0
	v_add_u32_e32 v42, s0, v70
	s_lshl_b32 s68, s2, 2
	v_ashrrev_i32_e32 v43, 31, v42
	v_lshl_add_u64 v[44:45], v[20:21], 0, s[68:69]
	v_lshlrev_b64 v[42:43], 12, v[42:43]
	v_lshl_add_u64 v[42:43], v[44:45], 0, v[42:43]
	v_add_co_u32_e32 v44, vcc, 0x2000, v42
	global_load_dword v35, v[42:43], off nt
	s_nop 0
	v_addc_co_u32_e32 v45, vcc, 0, v43, vcc
	global_load_dword v37, v[44:45], off nt
	v_add_co_u32_e32 v44, vcc, 0x4000, v42
	s_lshl_b32 s68, s0, 1
	s_nop 0
	v_addc_co_u32_e32 v45, vcc, 0, v43, vcc
	global_load_dword v39, v[44:45], off nt
	v_add_co_u32_e32 v44, vcc, 0x6000, v42
	s_nop 1
	v_addc_co_u32_e32 v45, vcc, 0, v43, vcc
	global_load_dword v41, v[44:45], off nt
	v_add_co_u32_e32 v44, vcc, 0x8000, v42
	s_nop 1
	v_addc_co_u32_e32 v45, vcc, 0, v43, vcc
	global_load_dword v46, v[44:45], off nt
	v_add_co_u32_e32 v44, vcc, 0xa000, v42
	s_nop 1
	v_addc_co_u32_e32 v45, vcc, 0, v43, vcc
	global_load_dword v47, v[44:45], off nt
	v_add_co_u32_e32 v44, vcc, 0xc000, v42
	s_nop 1
	v_addc_co_u32_e32 v45, vcc, 0, v43, vcc
	global_load_dword v48, v[44:45], off nt
	v_add_co_u32_e32 v44, vcc, 0xe000, v42
	s_nop 1
	v_addc_co_u32_e32 v45, vcc, 0, v43, vcc
	global_load_dword v49, v[44:45], off nt
	v_add_co_u32_e32 v44, vcc, 0x10000, v42
	s_nop 1
	v_addc_co_u32_e32 v45, vcc, 0, v43, vcc
	global_load_dword v50, v[44:45], off nt
	v_add_co_u32_e32 v44, vcc, 0x12000, v42
	s_nop 1
	v_addc_co_u32_e32 v45, vcc, 0, v43, vcc
	global_load_dword v51, v[44:45], off nt
	v_add_co_u32_e32 v44, vcc, 0x14000, v42
	s_nop 1
	v_addc_co_u32_e32 v45, vcc, 0, v43, vcc
	global_load_dword v52, v[44:45], off nt
	v_add_co_u32_e32 v44, vcc, 0x16000, v42
	s_nop 1
	v_addc_co_u32_e32 v45, vcc, 0, v43, vcc
	global_load_dword v53, v[44:45], off nt
	v_add_co_u32_e32 v44, vcc, 0x18000, v42
	s_nop 1
	v_addc_co_u32_e32 v45, vcc, 0, v43, vcc
	global_load_dword v54, v[44:45], off nt
	v_add_co_u32_e32 v44, vcc, 0x1a000, v42
	s_nop 1
	v_addc_co_u32_e32 v45, vcc, 0, v43, vcc
	global_load_dword v55, v[44:45], off nt
	v_add_co_u32_e32 v44, vcc, 0x1c000, v42
	s_nop 1
	v_addc_co_u32_e32 v45, vcc, 0, v43, vcc
	global_load_dword v56, v[44:45], off nt
	v_add_co_u32_e32 v44, vcc, 0x1e000, v42
	s_nop 1
	v_addc_co_u32_e32 v45, vcc, 0, v43, vcc
	global_load_dword v57, v[44:45], off nt
	v_add_co_u32_e32 v44, vcc, 0x20000, v42
	s_nop 1
	v_addc_co_u32_e32 v45, vcc, 0, v43, vcc
	global_load_dword v58, v[44:45], off nt
	v_add_co_u32_e32 v44, vcc, 0x22000, v42
	s_nop 1
	v_addc_co_u32_e32 v45, vcc, 0, v43, vcc
	global_load_dword v59, v[44:45], off nt
	v_add_co_u32_e32 v44, vcc, 0x24000, v42
	s_nop 1
	v_addc_co_u32_e32 v45, vcc, 0, v43, vcc
	global_load_dword v60, v[44:45], off nt
	v_add_co_u32_e32 v44, vcc, 0x26000, v42
	s_nop 1
	v_addc_co_u32_e32 v45, vcc, 0, v43, vcc
	global_load_dword v61, v[44:45], off nt
	v_add_co_u32_e32 v44, vcc, 0x28000, v42
	s_nop 1
	v_addc_co_u32_e32 v45, vcc, 0, v43, vcc
	global_load_dword v62, v[44:45], off nt
	v_add_co_u32_e32 v44, vcc, 0x2a000, v42
	s_nop 1
	v_addc_co_u32_e32 v45, vcc, 0, v43, vcc
	global_load_dword v63, v[44:45], off nt
	v_add_co_u32_e32 v44, vcc, 0x2c000, v42
	s_nop 1
	v_addc_co_u32_e32 v45, vcc, 0, v43, vcc
	global_load_dword v64, v[44:45], off nt
	v_add_co_u32_e32 v44, vcc, 0x2e000, v42
	s_nop 1
	v_addc_co_u32_e32 v45, vcc, 0, v43, vcc
	global_load_dword v65, v[44:45], off nt
	v_add_co_u32_e32 v44, vcc, 0x30000, v42
	s_nop 1
	v_addc_co_u32_e32 v45, vcc, 0, v43, vcc
	global_load_dword v66, v[44:45], off nt
	v_add_co_u32_e32 v44, vcc, 0x32000, v42
	s_nop 1
	v_addc_co_u32_e32 v45, vcc, 0, v43, vcc
	global_load_dword v67, v[44:45], off nt
	v_add_co_u32_e32 v44, vcc, 0x34000, v42
	s_nop 1
	v_addc_co_u32_e32 v45, vcc, 0, v43, vcc
	global_load_dword v68, v[44:45], off nt
	v_add_co_u32_e32 v44, vcc, 0x36000, v42
	s_nop 1
	v_addc_co_u32_e32 v45, vcc, 0, v43, vcc
	global_load_dword v69, v[44:45], off nt
	v_add_co_u32_e32 v44, vcc, 0x38000, v42
	s_nop 1
	v_addc_co_u32_e32 v45, vcc, 0, v43, vcc
	global_load_dword v86, v[44:45], off nt
	v_add_co_u32_e32 v44, vcc, 0x3a000, v42
	s_nop 1
	v_addc_co_u32_e32 v45, vcc, 0, v43, vcc
	global_load_dword v87, v[44:45], off nt
	v_add_co_u32_e32 v44, vcc, 0x3c000, v42
	s_nop 1
	v_addc_co_u32_e32 v45, vcc, 0, v43, vcc
	v_add_co_u32_e32 v42, vcc, 0x3e000, v42
	global_load_dword v44, v[44:45], off nt
	s_nop 0
	v_addc_co_u32_e32 v43, vcc, 0, v43, vcc
	global_load_dword v42, v[42:43], off nt
	s_waitcnt vmcnt(0)
; #define LAS __attribute__((address_space(3)))
; __device__ __forceinline__ unsigned cvt_pk(float lo, float hi) { f32x2_t v = {lo, hi}; bf16x2_t b = __builtin_convertvector(v, bf16x2_t); return __builtin_bit_cast(unsigned, b); }
; __device__ __forceinline__ unsigned pk_fp8x4(float a, float b, float c, float d) { int w = 0; w = __builtin_amdgcn_cvt_pk_fp8_f32(a, b, w, false); w = __builtin_amdgcn_cvt_pk_fp8_f32(c, d, w, true); return (unsigned)w; }
; template <bool F8 = false>
; __device__ __forceinline__ void p0_transpose_item(const float* W, int K, int N, bf16_t* WT, int k0, int n0, int drow0, const float* gs, LAS float* scr, int lane) {
;     ...
;     for (int i = 0; i < 32; ++i) scr[(2 * i + (lane >> 5)) * 33 + (lane & 31)] = wv[i];
;     asm volatile("s_waitcnt lgkmcnt(0)" ::: "memory");
;     const int c = lane & 7;
; #pragma unroll
;     for (int j = 0; j < 4; ++j) { const int n = (lane >> 3) + 8 * j; const LAS float* s = scr + (8 * c) * 33 + n;
;         if (F8) { u32x2 o8; o8.x = pk_fp8x4(32.f * s[0 * 33], 32.f * s[1 * 33], 32.f * s[2 * 33], 32.f * s[3 * 33]); o8.y = pk_fp8x4(32.f * s[4 * 33], 32.f * s[5 * 33], 32.f * s[6 * 33], 32.f * s[7 * 33]);
;             *(u32x2*)((unsigned char*)WT + (size_t)(drow0 + n) * K + k0 + 8 * c) = o8; }
;         else { u32x4 o; o.x = cvt_pk(s[0 * 33], s[1 * 33]); o.y = cvt_pk(s[2 * 33], s[3 * 33]); o.z = cvt_pk(s[4 * 33], s[5 * 33]); o.w = cvt_pk(s[6 * 33], s[7 * 33]);
;             *(u32x4*)(WT + (size_t)(drow0 + n) * K + k0 + 8 * c) = o; } }
	ds_write2_b32 v71, v35, v37 offset1:66
	ds_write2_b32 v71, v39, v41 offset0:132 offset1:198
	ds_write2_b32 v72, v46, v47 offset0:8 offset1:74
	ds_write2_b32 v72, v48, v49 offset0:140 offset1:206
	ds_write2_b32 v80, v50, v51 offset0:16 offset1:82
	ds_write2_b32 v80, v52, v53 offset0:148 offset1:214
	ds_write2_b32 v82, v54, v55 offset0:24 offset1:90
	ds_write2_b32 v82, v56, v57 offset0:156 offset1:222
	ds_write2_b32 v83, v58, v59 offset0:32 offset1:98
	ds_write2_b32 v83, v60, v61 offset0:164 offset1:230
	ds_write2_b32 v84, v62, v63 offset0:40 offset1:106
	ds_write2_b32 v84, v64, v65 offset0:172 offset1:238
	ds_write2_b32 v85, v66, v67 offset0:48 offset1:114
	ds_write2_b32 v85, v68, v69 offset0:180 offset1:246
	v_add_u32_e32 v35, 0x1c00, v71
	ds_write2_b32 v35, v86, v87 offset0:56 offset1:122
	ds_write2_b32 v35, v44, v42 offset0:188 offset1:254
	s_waitcnt lgkmcnt(0)
	ds_read2_b32 v[48:49], v76 offset0:33 offset1:41
	ds_read2_b32 v[50:51], v76 offset1:8
	ds_read2_b32 v[52:53], v76 offset0:66 offset1:74
	ds_read2_b32 v[54:55], v76 offset0:99 offset1:107
	ds_read2_b32 v[56:57], v76 offset0:132 offset1:140
	ds_read2_b32 v[58:59], v76 offset0:165 offset1:173
	ds_read2_b32 v[60:61], v76 offset0:198 offset1:206
	ds_read2_b32 v[62:63], v76 offset0:231 offset1:239
	v_ashrrev_i32_e32 v41, 31, v40
	v_lshl_add_u64 v[46:47], v[2:3], 0, s[68:69]
	v_lshlrev_b64 v[40:41], 13, v[40:41]
	v_ashrrev_i32_e32 v39, 31, v38
	s_waitcnt lgkmcnt(6)
	v_cvt_pk_bf16_f32 v42, v50, v48
	s_waitcnt lgkmcnt(4)
	v_cvt_pk_bf16_f32 v43, v52, v54
	s_waitcnt lgkmcnt(2)
	v_cvt_pk_bf16_f32 v44, v56, v58
	s_waitcnt lgkmcnt(0)
	v_cvt_pk_bf16_f32 v45, v60, v62
	v_lshl_add_u64 v[40:41], v[46:47], 0, v[40:41]
	v_lshlrev_b64 v[38:39], 13, v[38:39]
	global_store_dwordx4 v[40:41], v[42:45], off
	v_cvt_pk_bf16_f32 v40, v51, v49
	v_cvt_pk_bf16_f32 v41, v53, v55
	v_cvt_pk_bf16_f32 v42, v57, v59
	v_cvt_pk_bf16_f32 v43, v61, v63
	v_lshl_add_u64 v[38:39], v[46:47], 0, v[38:39]
	global_store_dwordx4 v[38:39], v[40:43], off
	ds_read2_b32 v[42:43], v76 offset0:16 offset1:24
	ds_read2_b32 v[44:45], v76 offset0:49 offset1:57
	ds_read2_b32 v[48:49], v76 offset0:82 offset1:90
	ds_read2_b32 v[50:51], v76 offset0:115 offset1:123
	ds_read2_b32 v[52:53], v76 offset0:148 offset1:156
	ds_read2_b32 v[54:55], v76 offset0:181 offset1:189
	ds_read2_b32 v[56:57], v76 offset0:214 offset1:222
	ds_read2_b32 v[58:59], v76 offset0:247 offset1:255
	v_ashrrev_i32_e32 v37, 31, v36
	v_lshlrev_b64 v[36:37], 13, v[36:37]
	v_ashrrev_i32_e32 v35, 31, v34
	s_waitcnt lgkmcnt(6)
	v_cvt_pk_bf16_f32 v38, v42, v44
	s_waitcnt lgkmcnt(4)
	v_cvt_pk_bf16_f32 v39, v48, v50
	s_waitcnt lgkmcnt(2)
	v_cvt_pk_bf16_f32 v40, v52, v54
	s_waitcnt lgkmcnt(0)
	v_cvt_pk_bf16_f32 v41, v56, v58
	v_lshl_add_u64 v[36:37], v[46:47], 0, v[36:37]
	v_lshlrev_b64 v[34:35], 13, v[34:35]
	global_store_dwordx4 v[36:37], v[38:41], off
	v_cvt_pk_bf16_f32 v36, v43, v45
	v_cvt_pk_bf16_f32 v37, v49, v51
	v_cvt_pk_bf16_f32 v38, v53, v55
	v_cvt_pk_bf16_f32 v39, v57, v59
	v_lshl_add_u64 v[34:35], v[46:47], 0, v[34:35]
	global_store_dwordx4 v[34:35], v[36:39], off
	s_waitcnt lgkmcnt(0)

; template <bool F8 = false>
; __device__ __forceinline__ void p0_transpose_item(const float* W, int K, int N, bf16_t* WT, int k0, int n0, int drow0, const float* gs, LAS float* scr, int lane) {
;     ...
;     for (int i = 0; i < 32; ++i) wv[i] = W[(size_t)(k0 + 2 * i + (lane >> 5)) * N + n0 + (lane & 31)];
;     if (gs) {
; #pragma unroll
;         for (int i = 0; i < 32; ++i) wv[i] *= gs[k0 + 2 * i + (lane >> 5)]; }
; #pragma unroll
;     for (int i = 0; i < 32; ++i) scr[(2 * i + (lane >> 5)) * 33 + (lane & 31)] = wv[i];
;     asm volatile("s_waitcnt lgkmcnt(0)" ::: "memory");
; template <int PART>
; __device__ __forceinline__ void phase0(const Ptrs& P, LAS float* scr, int gw, int NGW, int lane) {
;     ...
;         if (r < I_SQ) { const int nblk = DM / 32; p0_transpose_item(P.w_out, DM, DM, (bf16_t*)(ws + WS_WOUT), 64 * (r / nblk), 32 * (r % nblk), 32 * (r % nblk), nullptr, scr, lane); continue; } r -= I_SQ;
.LBB0_434:
	s_andn2_b64 vcc, exec, s[0:1]
	s_cbranch_vccnz .LBB0_436
	s_add_i32 s0, s9, 0x2800
	s_and_b32 s1, s0, 0x7fffffc0
	s_and_b32 s0, s8, 0x3e0
	v_add_u32_e32 v34, s1, v70
	s_lshl_b32 s68, s0, 2
	v_ashrrev_i32_e32 v35, 31, v34
	v_lshl_add_u64 v[36:37], v[26:27], 0, s[68:69]
	v_lshlrev_b64 v[34:35], 12, v[34:35]
	v_lshl_add_u64 v[34:35], v[36:37], 0, v[34:35]
	v_add_co_u32_e32 v36, vcc, 0x2000, v34
	global_load_dword v38, v[34:35], off nt
	s_nop 0
	v_addc_co_u32_e32 v37, vcc, 0, v35, vcc
	global_load_dword v39, v[36:37], off nt
	v_add_co_u32_e32 v36, vcc, 0x4000, v34
	s_lshl_b32 s68, s1, 1
	s_nop 0
	v_addc_co_u32_e32 v37, vcc, 0, v35, vcc
	global_load_dword v40, v[36:37], off nt
	v_add_co_u32_e32 v36, vcc, 0x6000, v34
	s_nop 1
	v_addc_co_u32_e32 v37, vcc, 0, v35, vcc
	global_load_dword v41, v[36:37], off nt
	v_add_co_u32_e32 v36, vcc, 0x8000, v34
	s_nop 1
	v_addc_co_u32_e32 v37, vcc, 0, v35, vcc
	global_load_dword v42, v[36:37], off nt
	v_add_co_u32_e32 v36, vcc, 0xa000, v34
	s_nop 1
	v_addc_co_u32_e32 v37, vcc, 0, v35, vcc
	global_load_dword v43, v[36:37], off nt
	v_add_co_u32_e32 v36, vcc, 0xc000, v34
	s_nop 1
	v_addc_co_u32_e32 v37, vcc, 0, v35, vcc
	global_load_dword v44, v[36:37], off nt
	v_add_co_u32_e32 v36, vcc, 0xe000, v34
	s_nop 1
	v_addc_co_u32_e32 v37, vcc, 0, v35, vcc
	global_load_dword v45, v[36:37], off nt
	v_add_co_u32_e32 v36, vcc, 0x10000, v34
	s_nop 1
	v_addc_co_u32_e32 v37, vcc, 0, v35, vcc
	global_load_dword v46, v[36:37], off nt
	v_add_co_u32_e32 v36, vcc, 0x12000, v34
	s_nop 1
	v_addc_co_u32_e32 v37, vcc, 0, v35, vcc
	global_load_dword v47, v[36:37], off nt
	v_add_co_u32_e32 v36, vcc, 0x14000, v34
	s_nop 1
	v_addc_co_u32_e32 v37, vcc, 0, v35, vcc
	global_load_dword v48, v[36:37], off nt
	v_add_co_u32_e32 v36, vcc, 0x16000, v34
	s_nop 1
	v_addc_co_u32_e32 v37, vcc, 0, v35, vcc
	global_load_dword v49, v[36:37], off nt
	v_add_co_u32_e32 v36, vcc, 0x18000, v34
	s_nop 1
	v_addc_co_u32_e32 v37, vcc, 0, v35, vcc
	global_load_dword v50, v[36:37], off nt
	v_add_co_u32_e32 v36, vcc, 0x1a000, v34
	s_nop 1
	v_addc_co_u32_e32 v37, vcc, 0, v35, vcc
	global_load_dword v51, v[36:37], off nt
	v_add_co_u32_e32 v36, vcc, 0x1c000, v34
	s_nop 1
	v_addc_co_u32_e32 v37, vcc, 0, v35, vcc
	global_load_dword v52, v[36:37], off nt
	v_add_co_u32_e32 v36, vcc, 0x1e000, v34
	s_nop 1
	v_addc_co_u32_e32 v37, vcc, 0, v35, vcc
	global_load_dword v53, v[36:37], off nt
	v_add_co_u32_e32 v36, vcc, 0x20000, v34
	s_nop 1
	v_addc_co_u32_e32 v37, vcc, 0, v35, vcc
	global_load_dword v54, v[36:37], off nt
	v_add_co_u32_e32 v36, vcc, 0x22000, v34
	s_nop 1
	v_addc_co_u32_e32 v37, vcc, 0, v35, vcc
	global_load_dword v55, v[36:37], off nt
	v_add_co_u32_e32 v36, vcc, 0x24000, v34
	s_nop 1
	v_addc_co_u32_e32 v37, vcc, 0, v35, vcc
	global_load_dword v56, v[36:37], off nt
	v_add_co_u32_e32 v36, vcc, 0x26000, v34
	s_nop 1
	v_addc_co_u32_e32 v37, vcc, 0, v35, vcc
	global_load_dword v57, v[36:37], off nt
	v_add_co_u32_e32 v36, vcc, 0x28000, v34
	s_nop 1
	v_addc_co_u32_e32 v37, vcc, 0, v35, vcc
	global_load_dword v58, v[36:37], off nt
	v_add_co_u32_e32 v36, vcc, 0x2a000, v34
	s_nop 1
	v_addc_co_u32_e32 v37, vcc, 0, v35, vcc
	global_load_dword v59, v[36:37], off nt
	v_add_co_u32_e32 v36, vcc, 0x2c000, v34
	s_nop 1
	v_addc_co_u32_e32 v37, vcc, 0, v35, vcc
	global_load_dword v60, v[36:37], off nt
	v_add_co_u32_e32 v36, vcc, 0x2e000, v34
	s_nop 1
	v_addc_co_u32_e32 v37, vcc, 0, v35, vcc
	global_load_dword v61, v[36:37], off nt
	v_add_co_u32_e32 v36, vcc, 0x30000, v34
	s_nop 1
	v_addc_co_u32_e32 v37, vcc, 0, v35, vcc
	global_load_dword v62, v[36:37], off nt
	v_add_co_u32_e32 v36, vcc, 0x32000, v34
	s_nop 1
	v_addc_co_u32_e32 v37, vcc, 0, v35, vcc
	global_load_dword v63, v[36:37], off nt
	v_add_co_u32_e32 v36, vcc, 0x34000, v34
	s_nop 1
	v_addc_co_u32_e32 v37, vcc, 0, v35, vcc
	global_load_dword v64, v[36:37], off nt
	v_add_co_u32_e32 v36, vcc, 0x36000, v34
	s_nop 1
	v_addc_co_u32_e32 v37, vcc, 0, v35, vcc
	global_load_dword v65, v[36:37], off nt
	v_add_co_u32_e32 v36, vcc, 0x38000, v34
	s_nop 1
	v_addc_co_u32_e32 v37, vcc, 0, v35, vcc
	global_load_dword v66, v[36:37], off nt
	v_add_co_u32_e32 v36, vcc, 0x3a000, v34
	s_nop 1
	v_addc_co_u32_e32 v37, vcc, 0, v35, vcc
	global_load_dword v67, v[36:37], off nt
	v_add_co_u32_e32 v36, vcc, 0x3c000, v34
	s_nop 1
	v_addc_co_u32_e32 v37, vcc, 0, v35, vcc
	v_add_co_u32_e32 v34, vcc, 0x3e000, v34
	global_load_dword v36, v[36:37], off nt
	s_nop 0
	v_addc_co_u32_e32 v35, vcc, 0, v35, vcc
	global_load_dword v34, v[34:35], off nt
	v_add_u32_e32 v35, 0x1c00, v71
	s_waitcnt vmcnt(0)
; #define LAS __attribute__((address_space(3)))
; __device__ __forceinline__ unsigned cvt_pk(float lo, float hi) { f32x2_t v = {lo, hi}; bf16x2_t b = __builtin_convertvector(v, bf16x2_t); return __builtin_bit_cast(unsigned, b); }
; __device__ __forceinline__ unsigned pk_fp8x4(float a, float b, float c, float d) { int w = 0; w = __builtin_amdgcn_cvt_pk_fp8_f32(a, b, w, false); w = __builtin_amdgcn_cvt_pk_fp8_f32(c, d, w, true); return (unsigned)w; }
; template <bool F8 = false>
; __device__ __forceinline__ void p0_transpose_item(const float* W, int K, int N, bf16_t* WT, int k0, int n0, int drow0, const float* gs, LAS float* scr, int lane) {
;     ...
;     for (int i = 0; i < 32; ++i) scr[(2 * i + (lane >> 5)) * 33 + (lane & 31)] = wv[i];
;     asm volatile("s_waitcnt lgkmcnt(0)" ::: "memory");
;     const int c = lane & 7;
; #pragma unroll
;     for (int j = 0; j < 4; ++j) { const int n = (lane >> 3) + 8 * j; const LAS float* s = scr + (8 * c) * 33 + n;
;         if (F8) { u32x2 o8; o8.x = pk_fp8x4(32.f * s[0 * 33], 32.f * s[1 * 33], 32.f * s[2 * 33], 32.f * s[3 * 33]); o8.y = pk_fp8x4(32.f * s[4 * 33], 32.f * s[5 * 33], 32.f * s[6 * 33], 32.f * s[7 * 33]);
;             *(u32x2*)((unsigned char*)WT + (size_t)(drow0 + n) * K + k0 + 8 * c) = o8; }
;         else { u32x4 o; o.x = cvt_pk(s[0 * 33], s[1 * 33]); o.y = cvt_pk(s[2 * 33], s[3 * 33]); o.z = cvt_pk(s[4 * 33], s[5 * 33]); o.w = cvt_pk(s[6 * 33], s[7 * 33]);
;             *(u32x4*)(WT + (size_t)(drow0 + n) * K + k0 + 8 * c) = o; } }
	ds_write2_b32 v71, v38, v39 offset1:66
	ds_write2_b32 v71, v40, v41 offset0:132 offset1:198
	ds_write2_b32 v72, v42, v43 offset0:8 offset1:74
	ds_write2_b32 v72, v44, v45 offset0:140 offset1:206
	ds_write2_b32 v80, v46, v47 offset0:16 offset1:82
	ds_write2_b32 v80, v48, v49 offset0:148 offset1:214
	ds_write2_b32 v82, v50, v51 offset0:24 offset1:90
	ds_write2_b32 v82, v52, v53 offset0:156 offset1:222
	ds_write2_b32 v83, v54, v55 offset0:32 offset1:98
	ds_write2_b32 v83, v56, v57 offset0:164 offset1:230
	ds_write2_b32 v84, v58, v59 offset0:40 offset1:106
	ds_write2_b32 v84, v60, v61 offset0:172 offset1:238
	ds_write2_b32 v85, v62, v63 offset0:48 offset1:114
	ds_write2_b32 v85, v64, v65 offset0:180 offset1:246
	ds_write2_b32 v35, v66, v67 offset0:56 offset1:122
	ds_write2_b32 v35, v36, v34 offset0:188 offset1:254
	s_waitcnt lgkmcnt(0)
	ds_read2_b32 v[40:41], v76 offset0:33 offset1:41
	ds_read2_b32 v[42:43], v76 offset1:8
	ds_read2_b32 v[44:45], v76 offset0:66 offset1:74
	ds_read2_b32 v[46:47], v76 offset0:99 offset1:107
	ds_read2_b32 v[48:49], v76 offset0:132 offset1:140
	ds_read2_b32 v[50:51], v76 offset0:165 offset1:173
	ds_read2_b32 v[52:53], v76 offset0:198 offset1:206
	ds_read2_b32 v[54:55], v76 offset0:231 offset1:239
	v_add_u32_e32 v56, s0, v75
	v_ashrrev_i32_e32 v57, 31, v56
	v_lshl_add_u64 v[38:39], v[8:9], 0, s[68:69]
	v_lshlrev_b64 v[56:57], 11, v[56:57]
	s_waitcnt lgkmcnt(6)
	v_cvt_pk_bf16_f32 v34, v42, v40
	s_waitcnt lgkmcnt(4)
	v_cvt_pk_bf16_f32 v35, v44, v46
	s_waitcnt lgkmcnt(2)
	v_cvt_pk_bf16_f32 v36, v48, v50
	s_waitcnt lgkmcnt(0)
	v_cvt_pk_bf16_f32 v37, v52, v54
	v_lshl_add_u64 v[56:57], v[38:39], 0, v[56:57]
	v_add_u32_e32 v40, s0, v77
	global_store_dwordx4 v[56:57], v[34:37], off
	v_add_u32_e32 v56, s0, v78
	v_ashrrev_i32_e32 v57, 31, v56
	v_cvt_pk_bf16_f32 v34, v43, v41
	v_ashrrev_i32_e32 v41, 31, v40
	v_lshlrev_b64 v[40:41], 11, v[40:41]
	v_cvt_pk_bf16_f32 v35, v45, v47
	v_cvt_pk_bf16_f32 v36, v49, v51
	v_cvt_pk_bf16_f32 v37, v53, v55
	v_lshl_add_u64 v[40:41], v[38:39], 0, v[40:41]
	global_store_dwordx4 v[40:41], v[34:37], off
	ds_read2_b32 v[40:41], v76 offset0:49 offset1:57
	ds_read2_b32 v[42:43], v76 offset0:16 offset1:24
	ds_read2_b32 v[44:45], v76 offset0:82 offset1:90
	ds_read2_b32 v[46:47], v76 offset0:115 offset1:123
	ds_read2_b32 v[48:49], v76 offset0:148 offset1:156
	ds_read2_b32 v[50:51], v76 offset0:181 offset1:189
	ds_read2_b32 v[52:53], v76 offset0:214 offset1:222
	ds_read2_b32 v[54:55], v76 offset0:247 offset1:255
	v_lshlrev_b64 v[56:57], 11, v[56:57]
	s_waitcnt lgkmcnt(6)
	v_cvt_pk_bf16_f32 v34, v42, v40
	s_waitcnt lgkmcnt(4)
	v_cvt_pk_bf16_f32 v35, v44, v46
	s_waitcnt lgkmcnt(2)
	v_cvt_pk_bf16_f32 v36, v48, v50
	s_waitcnt lgkmcnt(0)
	v_cvt_pk_bf16_f32 v37, v52, v54
	v_lshl_add_u64 v[56:57], v[38:39], 0, v[56:57]
	v_add_u32_e32 v40, s0, v79
	global_store_dwordx4 v[56:57], v[34:37], off
	s_nop 1
	v_cvt_pk_bf16_f32 v34, v43, v41
	v_ashrrev_i32_e32 v41, 31, v40
	v_lshlrev_b64 v[40:41], 11, v[40:41]
	v_cvt_pk_bf16_f32 v35, v45, v47
	v_cvt_pk_bf16_f32 v36, v49, v51
	v_cvt_pk_bf16_f32 v37, v53, v55
	v_lshl_add_u64 v[38:39], v[38:39], 0, v[40:41]
	global_store_dwordx4 v[38:39], v[34:37], off
	s_waitcnt lgkmcnt(0)

; template <bool F8 = false>
; __device__ __forceinline__ void p0_transpose_item(const float* W, int K, int N, bf16_t* WT, int k0, int n0, int drow0, const float* gs, LAS float* scr, int lane) {
;     ...
;     for (int i = 0; i < 32; ++i) wv[i] = W[(size_t)(k0 + 2 * i + (lane >> 5)) * N + n0 + (lane & 31)];
;     if (gs) {
; #pragma unroll
;         for (int i = 0; i < 32; ++i) wv[i] *= gs[k0 + 2 * i + (lane >> 5)]; }
; #pragma unroll
;     for (int i = 0; i < 32; ++i) scr[(2 * i + (lane >> 5)) * 33 + (lane & 31)] = wv[i];
;     asm volatile("s_waitcnt lgkmcnt(0)" ::: "memory");
; template <int PART>
; __device__ __forceinline__ void phase0(const Ptrs& P, LAS float* scr, int gw, int NGW, int lane) {
;     ...
;         if (r < I_SQ) { const int nblk = DM / 32; p0_transpose_item(P.w_bra, DM, DM, (bf16_t*)(ws + WS_WBRA), 64 * (r / nblk), 32 * (r % nblk), 32 * (r % nblk), nullptr, scr, lane); continue; } r -= I_SQ;
.LBB0_437:
	s_andn2_b64 vcc, exec, s[0:1]
	s_cbranch_vccnz .LBB0_439
	s_add_i32 s0, s9, 0x2c00
	s_and_b32 s1, s0, 0x7fffffc0
	s_and_b32 s0, s8, 0x3e0
	v_add_u32_e32 v34, s1, v70
	s_lshl_b32 s68, s0, 2
	v_ashrrev_i32_e32 v35, 31, v34
	v_lshl_add_u64 v[36:37], v[28:29], 0, s[68:69]
	v_lshlrev_b64 v[34:35], 12, v[34:35]
	v_lshl_add_u64 v[34:35], v[36:37], 0, v[34:35]
	v_add_co_u32_e32 v36, vcc, 0x2000, v34
	global_load_dword v38, v[34:35], off nt
	s_nop 0
	v_addc_co_u32_e32 v37, vcc, 0, v35, vcc
	global_load_dword v39, v[36:37], off nt
	v_add_co_u32_e32 v36, vcc, 0x4000, v34
	s_lshl_b32 s68, s1, 1
	s_nop 0
	v_addc_co_u32_e32 v37, vcc, 0, v35, vcc
	global_load_dword v40, v[36:37], off nt
	v_add_co_u32_e32 v36, vcc, 0x6000, v34
	s_nop 1
	v_addc_co_u32_e32 v37, vcc, 0, v35, vcc
	global_load_dword v41, v[36:37], off nt
	v_add_co_u32_e32 v36, vcc, 0x8000, v34
	s_nop 1
	v_addc_co_u32_e32 v37, vcc, 0, v35, vcc
	global_load_dword v42, v[36:37], off nt
	v_add_co_u32_e32 v36, vcc, 0xa000, v34
	s_nop 1
	v_addc_co_u32_e32 v37, vcc, 0, v35, vcc
	global_load_dword v43, v[36:37], off nt
	v_add_co_u32_e32 v36, vcc, 0xc000, v34
	s_nop 1
	v_addc_co_u32_e32 v37, vcc, 0, v35, vcc
	global_load_dword v44, v[36:37], off nt
	v_add_co_u32_e32 v36, vcc, 0xe000, v34
	s_nop 1
	v_addc_co_u32_e32 v37, vcc, 0, v35, vcc
	global_load_dword v45, v[36:37], off nt
	v_add_co_u32_e32 v36, vcc, 0x10000, v34
	s_nop 1
	v_addc_co_u32_e32 v37, vcc, 0, v35, vcc
	global_load_dword v46, v[36:37], off nt
	v_add_co_u32_e32 v36, vcc, 0x12000, v34
	s_nop 1
	v_addc_co_u32_e32 v37, vcc, 0, v35, vcc
	global_load_dword v47, v[36:37], off nt
	v_add_co_u32_e32 v36, vcc, 0x14000, v34
	s_nop 1
	v_addc_co_u32_e32 v37, vcc, 0, v35, vcc
	global_load_dword v48, v[36:37], off nt
	v_add_co_u32_e32 v36, vcc, 0x16000, v34
	s_nop 1
	v_addc_co_u32_e32 v37, vcc, 0, v35, vcc
	global_load_dword v49, v[36:37], off nt
	v_add_co_u32_e32 v36, vcc, 0x18000, v34
	s_nop 1
	v_addc_co_u32_e32 v37, vcc, 0, v35, vcc
	global_load_dword v50, v[36:37], off nt
	v_add_co_u32_e32 v36, vcc, 0x1a000, v34
	s_nop 1
	v_addc_co_u32_e32 v37, vcc, 0, v35, vcc
	global_load_dword v51, v[36:37], off nt
	v_add_co_u32_e32 v36, vcc, 0x1c000, v34
	s_nop 1
	v_addc_co_u32_e32 v37, vcc, 0, v35, vcc
	global_load_dword v52, v[36:37], off nt
	v_add_co_u32_e32 v36, vcc, 0x1e000, v34
	s_nop 1
	v_addc_co_u32_e32 v37, vcc, 0, v35, vcc
	global_load_dword v53, v[36:37], off nt
	v_add_co_u32_e32 v36, vcc, 0x20000, v34
	s_nop 1
	v_addc_co_u32_e32 v37, vcc, 0, v35, vcc
	global_load_dword v54, v[36:37], off nt
	v_add_co_u32_e32 v36, vcc, 0x22000, v34
	s_nop 1
	v_addc_co_u32_e32 v37, vcc, 0, v35, vcc
	global_load_dword v55, v[36:37], off nt
	v_add_co_u32_e32 v36, vcc, 0x24000, v34
	s_nop 1
	v_addc_co_u32_e32 v37, vcc, 0, v35, vcc
	global_load_dword v56, v[36:37], off nt
	v_add_co_u32_e32 v36, vcc, 0x26000, v34
	s_nop 1
	v_addc_co_u32_e32 v37, vcc, 0, v35, vcc
	global_load_dword v57, v[36:37], off nt
	v_add_co_u32_e32 v36, vcc, 0x28000, v34
	s_nop 1
	v_addc_co_u32_e32 v37, vcc, 0, v35, vcc
	global_load_dword v58, v[36:37], off nt
	v_add_co_u32_e32 v36, vcc, 0x2a000, v34
	s_nop 1
	v_addc_co_u32_e32 v37, vcc, 0, v35, vcc
	global_load_dword v59, v[36:37], off nt
	v_add_co_u32_e32 v36, vcc, 0x2c000, v34
	s_nop 1
	v_addc_co_u32_e32 v37, vcc, 0, v35, vcc
	global_load_dword v60, v[36:37], off nt
	v_add_co_u32_e32 v36, vcc, 0x2e000, v34
	s_nop 1
	v_addc_co_u32_e32 v37, vcc, 0, v35, vcc
	global_load_dword v61, v[36:37], off nt
	v_add_co_u32_e32 v36, vcc, 0x30000, v34
	s_nop 1
	v_addc_co_u32_e32 v37, vcc, 0, v35, vcc
	global_load_dword v62, v[36:37], off nt
	v_add_co_u32_e32 v36, vcc, 0x32000, v34
	s_nop 1
	v_addc_co_u32_e32 v37, vcc, 0, v35, vcc
	global_load_dword v63, v[36:37], off nt
	v_add_co_u32_e32 v36, vcc, 0x34000, v34
	s_nop 1
	v_addc_co_u32_e32 v37, vcc, 0, v35, vcc
	global_load_dword v64, v[36:37], off nt
	v_add_co_u32_e32 v36, vcc, 0x36000, v34
	s_nop 1
	v_addc_co_u32_e32 v37, vcc, 0, v35, vcc
	global_load_dword v65, v[36:37], off nt
	v_add_co_u32_e32 v36, vcc, 0x38000, v34
	s_nop 1
	v_addc_co_u32_e32 v37, vcc, 0, v35, vcc
	global_load_dword v66, v[36:37], off nt
	v_add_co_u32_e32 v36, vcc, 0x3a000, v34
	s_nop 1
	v_addc_co_u32_e32 v37, vcc, 0, v35, vcc
	global_load_dword v67, v[36:37], off nt
	v_add_co_u32_e32 v36, vcc, 0x3c000, v34
	s_nop 1
	v_addc_co_u32_e32 v37, vcc, 0, v35, vcc
	v_add_co_u32_e32 v34, vcc, 0x3e000, v34
	global_load_dword v36, v[36:37], off nt
	s_nop 0
	v_addc_co_u32_e32 v35, vcc, 0, v35, vcc
	global_load_dword v34, v[34:35], off nt
	v_add_u32_e32 v35, 0x1c00, v71
	s_waitcnt vmcnt(0)
; #define LAS __attribute__((address_space(3)))
; __device__ __forceinline__ unsigned cvt_pk(float lo, float hi) { f32x2_t v = {lo, hi}; bf16x2_t b = __builtin_convertvector(v, bf16x2_t); return __builtin_bit_cast(unsigned, b); }
; __device__ __forceinline__ unsigned pk_fp8x4(float a, float b, float c, float d) { int w = 0; w = __builtin_amdgcn_cvt_pk_fp8_f32(a, b, w, false); w = __builtin_amdgcn_cvt_pk_fp8_f32(c, d, w, true); return (unsigned)w; }
; template <bool F8 = false>
; __device__ __forceinline__ void p0_transpose_item(const float* W, int K, int N, bf16_t* WT, int k0, int n0, int drow0, const float* gs, LAS float* scr, int lane) {
;     ...
;     for (int i = 0; i < 32; ++i) scr[(2 * i + (lane >> 5)) * 33 + (lane & 31)] = wv[i];
;     asm volatile("s_waitcnt lgkmcnt(0)" ::: "memory");
;     const int c = lane & 7;
; #pragma unroll
;     for (int j = 0; j < 4; ++j) { const int n = (lane >> 3) + 8 * j; const LAS float* s = scr + (8 * c) * 33 + n;
;         if (F8) { u32x2 o8; o8.x = pk_fp8x4(32.f * s[0 * 33], 32.f * s[1 * 33], 32.f * s[2 * 33], 32.f * s[3 * 33]); o8.y = pk_fp8x4(32.f * s[4 * 33], 32.f * s[5 * 33], 32.f * s[6 * 33], 32.f * s[7 * 33]);
;             *(u32x2*)((unsigned char*)WT + (size_t)(drow0 + n) * K + k0 + 8 * c) = o8; }
;         else { u32x4 o; o.x = cvt_pk(s[0 * 33], s[1 * 33]); o.y = cvt_pk(s[2 * 33], s[3 * 33]); o.z = cvt_pk(s[4 * 33], s[5 * 33]); o.w = cvt_pk(s[6 * 33], s[7 * 33]);
;             *(u32x4*)(WT + (size_t)(drow0 + n) * K + k0 + 8 * c) = o; } }
	ds_write2_b32 v71, v38, v39 offset1:66
	ds_write2_b32 v71, v40, v41 offset0:132 offset1:198
	ds_write2_b32 v72, v42, v43 offset0:8 offset1:74
	ds_write2_b32 v72, v44, v45 offset0:140 offset1:206
	ds_write2_b32 v80, v46, v47 offset0:16 offset1:82
	ds_write2_b32 v80, v48, v49 offset0:148 offset1:214
	ds_write2_b32 v82, v50, v51 offset0:24 offset1:90
	ds_write2_b32 v82, v52, v53 offset0:156 offset1:222
	ds_write2_b32 v83, v54, v55 offset0:32 offset1:98
	ds_write2_b32 v83, v56, v57 offset0:164 offset1:230
	ds_write2_b32 v84, v58, v59 offset0:40 offset1:106
	ds_write2_b32 v84, v60, v61 offset0:172 offset1:238
	ds_write2_b32 v85, v62, v63 offset0:48 offset1:114
	ds_write2_b32 v85, v64, v65 offset0:180 offset1:246
	ds_write2_b32 v35, v66, v67 offset0:56 offset1:122
	ds_write2_b32 v35, v36, v34 offset0:188 offset1:254
	s_waitcnt lgkmcnt(0)
	ds_read2_b32 v[40:41], v76 offset0:33 offset1:41
	ds_read2_b32 v[42:43], v76 offset1:8
	ds_read2_b32 v[44:45], v76 offset0:66 offset1:74
	ds_read2_b32 v[46:47], v76 offset0:99 offset1:107
	ds_read2_b32 v[48:49], v76 offset0:132 offset1:140
	ds_read2_b32 v[50:51], v76 offset0:165 offset1:173
	ds_read2_b32 v[52:53], v76 offset0:198 offset1:206
	ds_read2_b32 v[54:55], v76 offset0:231 offset1:239
	v_add_u32_e32 v56, s0, v75
	v_ashrrev_i32_e32 v57, 31, v56
	v_lshl_add_u64 v[38:39], v[10:11], 0, s[68:69]
	v_lshlrev_b64 v[56:57], 11, v[56:57]
	s_waitcnt lgkmcnt(6)
	v_cvt_pk_bf16_f32 v34, v42, v40
	s_waitcnt lgkmcnt(4)
	v_cvt_pk_bf16_f32 v35, v44, v46
	s_waitcnt lgkmcnt(2)
	v_cvt_pk_bf16_f32 v36, v48, v50
	s_waitcnt lgkmcnt(0)
	v_cvt_pk_bf16_f32 v37, v52, v54
	v_lshl_add_u64 v[56:57], v[38:39], 0, v[56:57]
	v_add_u32_e32 v40, s0, v77
	global_store_dwordx4 v[56:57], v[34:37], off
	v_add_u32_e32 v56, s0, v78
	v_ashrrev_i32_e32 v57, 31, v56
	v_cvt_pk_bf16_f32 v34, v43, v41
	v_ashrrev_i32_e32 v41, 31, v40
	v_lshlrev_b64 v[40:41], 11, v[40:41]
	v_cvt_pk_bf16_f32 v35, v45, v47
	v_cvt_pk_bf16_f32 v36, v49, v51
	v_cvt_pk_bf16_f32 v37, v53, v55
	v_lshl_add_u64 v[40:41], v[38:39], 0, v[40:41]
	global_store_dwordx4 v[40:41], v[34:37], off
	ds_read2_b32 v[40:41], v76 offset0:49 offset1:57
	ds_read2_b32 v[42:43], v76 offset0:16 offset1:24
	ds_read2_b32 v[44:45], v76 offset0:82 offset1:90
	ds_read2_b32 v[46:47], v76 offset0:115 offset1:123
	ds_read2_b32 v[48:49], v76 offset0:148 offset1:156
	ds_read2_b32 v[50:51], v76 offset0:181 offset1:189
	ds_read2_b32 v[52:53], v76 offset0:214 offset1:222
	ds_read2_b32 v[54:55], v76 offset0:247 offset1:255
	v_lshlrev_b64 v[56:57], 11, v[56:57]
	s_waitcnt lgkmcnt(6)
	v_cvt_pk_bf16_f32 v34, v42, v40
	s_waitcnt lgkmcnt(4)
	v_cvt_pk_bf16_f32 v35, v44, v46
	s_waitcnt lgkmcnt(2)
	v_cvt_pk_bf16_f32 v36, v48, v50
	s_waitcnt lgkmcnt(0)
	v_cvt_pk_bf16_f32 v37, v52, v54
	v_lshl_add_u64 v[56:57], v[38:39], 0, v[56:57]
	v_add_u32_e32 v40, s0, v79
	global_store_dwordx4 v[56:57], v[34:37], off
	s_nop 1
	v_cvt_pk_bf16_f32 v34, v43, v41
	v_ashrrev_i32_e32 v41, 31, v40
	v_lshlrev_b64 v[40:41], 11, v[40:41]
	v_cvt_pk_bf16_f32 v35, v45, v47
	v_cvt_pk_bf16_f32 v36, v49, v51
	v_cvt_pk_bf16_f32 v37, v53, v55
	v_lshl_add_u64 v[38:39], v[38:39], 0, v[40:41]
	global_store_dwordx4 v[38:39], v[34:37], off
	s_waitcnt lgkmcnt(0)

; template <bool F8 = false>
; __device__ __forceinline__ void p0_transpose_item(const float* W, int K, int N, bf16_t* WT, int k0, int n0, int drow0, const float* gs, LAS float* scr, int lane) {
;     ...
;     for (int i = 0; i < 32; ++i) wv[i] = W[(size_t)(k0 + 2 * i + (lane >> 5)) * N + n0 + (lane & 31)];
;     if (gs) {
; #pragma unroll
;         for (int i = 0; i < 32; ++i) wv[i] *= gs[k0 + 2 * i + (lane >> 5)]; }
; #pragma unroll
;     for (int i = 0; i < 32; ++i) scr[(2 * i + (lane >> 5)) * 33 + (lane & 31)] = wv[i];
;     asm volatile("s_waitcnt lgkmcnt(0)" ::: "memory");
; template <int PART>
; __device__ __forceinline__ void phase0(const Ptrs& P, LAS float* scr, int gw, int NGW, int lane) {
;     ...
;         if (r < I_SQ) { const int nblk = DM / 32; p0_transpose_item(P.w_brl, DM, DM, (bf16_t*)(ws + WS_WBRL), 64 * (r / nblk), 32 * (r % nblk), 32 * (r % nblk), nullptr, scr, lane); continue; } r -= I_SQ;
.LBB0_440:
	s_andn2_b64 vcc, exec, s[0:1]
	s_cbranch_vccnz .LBB0_442
	s_add_i32 s0, s9, 0x80003000
	s_and_b32 s1, s0, 0x3c0
	s_and_b32 s0, s8, 0x3e0
	v_add_u32_e32 v34, s1, v70
	s_lshl_b32 s68, s0, 2
	v_ashrrev_i32_e32 v35, 31, v34
	v_lshl_add_u64 v[36:37], v[30:31], 0, s[68:69]
	v_lshlrev_b64 v[34:35], 12, v[34:35]
	v_lshl_add_u64 v[34:35], v[36:37], 0, v[34:35]
	v_add_co_u32_e32 v36, vcc, 0x2000, v34
	global_load_dword v38, v[34:35], off nt
	s_nop 0
	v_addc_co_u32_e32 v37, vcc, 0, v35, vcc
	global_load_dword v39, v[36:37], off nt
	v_add_co_u32_e32 v36, vcc, 0x4000, v34
	s_lshl_b32 s68, s1, 1
	s_nop 0
	v_addc_co_u32_e32 v37, vcc, 0, v35, vcc
	global_load_dword v40, v[36:37], off nt
	v_add_co_u32_e32 v36, vcc, 0x6000, v34
	s_nop 1
	v_addc_co_u32_e32 v37, vcc, 0, v35, vcc
	global_load_dword v41, v[36:37], off nt
	v_add_co_u32_e32 v36, vcc, 0x8000, v34
	s_nop 1
	v_addc_co_u32_e32 v37, vcc, 0, v35, vcc
	global_load_dword v42, v[36:37], off nt
	v_add_co_u32_e32 v36, vcc, 0xa000, v34
	s_nop 1
	v_addc_co_u32_e32 v37, vcc, 0, v35, vcc
	global_load_dword v43, v[36:37], off nt
	v_add_co_u32_e32 v36, vcc, 0xc000, v34
	s_nop 1
	v_addc_co_u32_e32 v37, vcc, 0, v35, vcc
	global_load_dword v44, v[36:37], off nt
	v_add_co_u32_e32 v36, vcc, 0xe000, v34
	s_nop 1
	v_addc_co_u32_e32 v37, vcc, 0, v35, vcc
	global_load_dword v45, v[36:37], off nt
	v_add_co_u32_e32 v36, vcc, 0x10000, v34
	s_nop 1
	v_addc_co_u32_e32 v37, vcc, 0, v35, vcc
	global_load_dword v46, v[36:37], off nt
	v_add_co_u32_e32 v36, vcc, 0x12000, v34
	s_nop 1
	v_addc_co_u32_e32 v37, vcc, 0, v35, vcc
	global_load_dword v47, v[36:37], off nt
	v_add_co_u32_e32 v36, vcc, 0x14000, v34
	s_nop 1
	v_addc_co_u32_e32 v37, vcc, 0, v35, vcc
	global_load_dword v48, v[36:37], off nt
	v_add_co_u32_e32 v36, vcc, 0x16000, v34
	s_nop 1
	v_addc_co_u32_e32 v37, vcc, 0, v35, vcc
	global_load_dword v49, v[36:37], off nt
	v_add_co_u32_e32 v36, vcc, 0x18000, v34
	s_nop 1
	v_addc_co_u32_e32 v37, vcc, 0, v35, vcc
	global_load_dword v50, v[36:37], off nt
	v_add_co_u32_e32 v36, vcc, 0x1a000, v34
	s_nop 1
	v_addc_co_u32_e32 v37, vcc, 0, v35, vcc
	global_load_dword v51, v[36:37], off nt
	v_add_co_u32_e32 v36, vcc, 0x1c000, v34
	s_nop 1
	v_addc_co_u32_e32 v37, vcc, 0, v35, vcc
	global_load_dword v52, v[36:37], off nt
	v_add_co_u32_e32 v36, vcc, 0x1e000, v34
	s_nop 1
	v_addc_co_u32_e32 v37, vcc, 0, v35, vcc
	global_load_dword v53, v[36:37], off nt
	v_add_co_u32_e32 v36, vcc, 0x20000, v34
	s_nop 1
	v_addc_co_u32_e32 v37, vcc, 0, v35, vcc
	global_load_dword v54, v[36:37], off nt
	v_add_co_u32_e32 v36, vcc, 0x22000, v34
	s_nop 1
	v_addc_co_u32_e32 v37, vcc, 0, v35, vcc
	global_load_dword v55, v[36:37], off nt
	v_add_co_u32_e32 v36, vcc, 0x24000, v34
	s_nop 1
	v_addc_co_u32_e32 v37, vcc, 0, v35, vcc
	global_load_dword v56, v[36:37], off nt
	v_add_co_u32_e32 v36, vcc, 0x26000, v34
	s_nop 1
	v_addc_co_u32_e32 v37, vcc, 0, v35, vcc
	global_load_dword v57, v[36:37], off nt
	v_add_co_u32_e32 v36, vcc, 0x28000, v34
	s_nop 1
	v_addc_co_u32_e32 v37, vcc, 0, v35, vcc
	global_load_dword v58, v[36:37], off nt
	v_add_co_u32_e32 v36, vcc, 0x2a000, v34
	s_nop 1
	v_addc_co_u32_e32 v37, vcc, 0, v35, vcc
	global_load_dword v59, v[36:37], off nt
	v_add_co_u32_e32 v36, vcc, 0x2c000, v34
	s_nop 1
	v_addc_co_u32_e32 v37, vcc, 0, v35, vcc
	global_load_dword v60, v[36:37], off nt
	v_add_co_u32_e32 v36, vcc, 0x2e000, v34
	s_nop 1
	v_addc_co_u32_e32 v37, vcc, 0, v35, vcc
	global_load_dword v61, v[36:37], off nt
	v_add_co_u32_e32 v36, vcc, 0x30000, v34
	s_nop 1
	v_addc_co_u32_e32 v37, vcc, 0, v35, vcc
	global_load_dword v62, v[36:37], off nt
	v_add_co_u32_e32 v36, vcc, 0x32000, v34
	s_nop 1
	v_addc_co_u32_e32 v37, vcc, 0, v35, vcc
	global_load_dword v63, v[36:37], off nt
	v_add_co_u32_e32 v36, vcc, 0x34000, v34
	s_nop 1
	v_addc_co_u32_e32 v37, vcc, 0, v35, vcc
	global_load_dword v64, v[36:37], off nt
	v_add_co_u32_e32 v36, vcc, 0x36000, v34
	s_nop 1
	v_addc_co_u32_e32 v37, vcc, 0, v35, vcc
	global_load_dword v65, v[36:37], off nt
	v_add_co_u32_e32 v36, vcc, 0x38000, v34
	s_nop 1
	v_addc_co_u32_e32 v37, vcc, 0, v35, vcc
	global_load_dword v66, v[36:37], off nt
	v_add_co_u32_e32 v36, vcc, 0x3a000, v34
	s_nop 1
	v_addc_co_u32_e32 v37, vcc, 0, v35, vcc
	global_load_dword v67, v[36:37], off nt
	v_add_co_u32_e32 v36, vcc, 0x3c000, v34
	s_nop 1
	v_addc_co_u32_e32 v37, vcc, 0, v35, vcc
	v_add_co_u32_e32 v34, vcc, 0x3e000, v34
	global_load_dword v36, v[36:37], off nt
	s_nop 0
	v_addc_co_u32_e32 v35, vcc, 0, v35, vcc
	global_load_dword v34, v[34:35], off nt
	v_add_u32_e32 v35, 0x1c00, v71
	s_waitcnt vmcnt(0)
; #define LAS __attribute__((address_space(3)))
; __device__ __forceinline__ unsigned cvt_pk(float lo, float hi) { f32x2_t v = {lo, hi}; bf16x2_t b = __builtin_convertvector(v, bf16x2_t); return __builtin_bit_cast(unsigned, b); }
; __device__ __forceinline__ unsigned pk_fp8x4(float a, float b, float c, float d) { int w = 0; w = __builtin_amdgcn_cvt_pk_fp8_f32(a, b, w, false); w = __builtin_amdgcn_cvt_pk_fp8_f32(c, d, w, true); return (unsigned)w; }
; template <bool F8 = false>
; __device__ __forceinline__ void p0_transpose_item(const float* W, int K, int N, bf16_t* WT, int k0, int n0, int drow0, const float* gs, LAS float* scr, int lane) {
;     ...
;     for (int i = 0; i < 32; ++i) scr[(2 * i + (lane >> 5)) * 33 + (lane & 31)] = wv[i];
;     asm volatile("s_waitcnt lgkmcnt(0)" ::: "memory");
;     const int c = lane & 7;
; #pragma unroll
;     for (int j = 0; j < 4; ++j) { const int n = (lane >> 3) + 8 * j; const LAS float* s = scr + (8 * c) * 33 + n;
;         if (F8) { u32x2 o8; o8.x = pk_fp8x4(32.f * s[0 * 33], 32.f * s[1 * 33], 32.f * s[2 * 33], 32.f * s[3 * 33]); o8.y = pk_fp8x4(32.f * s[4 * 33], 32.f * s[5 * 33], 32.f * s[6 * 33], 32.f * s[7 * 33]);
;             *(u32x2*)((unsigned char*)WT + (size_t)(drow0 + n) * K + k0 + 8 * c) = o8; }
;         else { u32x4 o; o.x = cvt_pk(s[0 * 33], s[1 * 33]); o.y = cvt_pk(s[2 * 33], s[3 * 33]); o.z = cvt_pk(s[4 * 33], s[5 * 33]); o.w = cvt_pk(s[6 * 33], s[7 * 33]);
;             *(u32x4*)(WT + (size_t)(drow0 + n) * K + k0 + 8 * c) = o; } }
	ds_write2_b32 v71, v38, v39 offset1:66
	ds_write2_b32 v71, v40, v41 offset0:132 offset1:198
	ds_write2_b32 v72, v42, v43 offset0:8 offset1:74
	ds_write2_b32 v72, v44, v45 offset0:140 offset1:206
	ds_write2_b32 v80, v46, v47 offset0:16 offset1:82
	ds_write2_b32 v80, v48, v49 offset0:148 offset1:214
	ds_write2_b32 v82, v50, v51 offset0:24 offset1:90
	ds_write2_b32 v82, v52, v53 offset0:156 offset1:222
	ds_write2_b32 v83, v54, v55 offset0:32 offset1:98
	ds_write2_b32 v83, v56, v57 offset0:164 offset1:230
	ds_write2_b32 v84, v58, v59 offset0:40 offset1:106
	ds_write2_b32 v84, v60, v61 offset0:172 offset1:238
	ds_write2_b32 v85, v62, v63 offset0:48 offset1:114
	ds_write2_b32 v85, v64, v65 offset0:180 offset1:246
	ds_write2_b32 v35, v66, v67 offset0:56 offset1:122
	ds_write2_b32 v35, v36, v34 offset0:188 offset1:254
	s_waitcnt lgkmcnt(0)
	ds_read2_b32 v[40:41], v76 offset0:33 offset1:41
	ds_read2_b32 v[42:43], v76 offset1:8
	ds_read2_b32 v[44:45], v76 offset0:66 offset1:74
	ds_read2_b32 v[46:47], v76 offset0:99 offset1:107
	ds_read2_b32 v[48:49], v76 offset0:132 offset1:140
	ds_read2_b32 v[50:51], v76 offset0:165 offset1:173
	ds_read2_b32 v[52:53], v76 offset0:198 offset1:206
	ds_read2_b32 v[54:55], v76 offset0:231 offset1:239
	v_add_u32_e32 v56, s0, v75
	v_ashrrev_i32_e32 v57, 31, v56
	v_lshl_add_u64 v[38:39], v[12:13], 0, s[68:69]
	v_lshlrev_b64 v[56:57], 11, v[56:57]
	s_waitcnt lgkmcnt(6)
	v_cvt_pk_bf16_f32 v34, v42, v40
	s_waitcnt lgkmcnt(4)
	v_cvt_pk_bf16_f32 v35, v44, v46
	s_waitcnt lgkmcnt(2)
	v_cvt_pk_bf16_f32 v36, v48, v50
	s_waitcnt lgkmcnt(0)
	v_cvt_pk_bf16_f32 v37, v52, v54
	v_lshl_add_u64 v[56:57], v[38:39], 0, v[56:57]
	v_add_u32_e32 v40, s0, v77
	global_store_dwordx4 v[56:57], v[34:37], off
	v_add_u32_e32 v56, s0, v78
	v_ashrrev_i32_e32 v57, 31, v56
	v_cvt_pk_bf16_f32 v34, v43, v41
	v_ashrrev_i32_e32 v41, 31, v40
	v_lshlrev_b64 v[40:41], 11, v[40:41]
	v_cvt_pk_bf16_f32 v35, v45, v47
	v_cvt_pk_bf16_f32 v36, v49, v51
	v_cvt_pk_bf16_f32 v37, v53, v55
	v_lshl_add_u64 v[40:41], v[38:39], 0, v[40:41]
	global_store_dwordx4 v[40:41], v[34:37], off
	ds_read2_b32 v[40:41], v76 offset0:49 offset1:57
	ds_read2_b32 v[42:43], v76 offset0:16 offset1:24
	ds_read2_b32 v[44:45], v76 offset0:82 offset1:90
	ds_read2_b32 v[46:47], v76 offset0:115 offset1:123
	ds_read2_b32 v[48:49], v76 offset0:148 offset1:156
	ds_read2_b32 v[50:51], v76 offset0:181 offset1:189
	ds_read2_b32 v[52:53], v76 offset0:214 offset1:222
	ds_read2_b32 v[54:55], v76 offset0:247 offset1:255
	v_lshlrev_b64 v[56:57], 11, v[56:57]
	s_waitcnt lgkmcnt(6)
	v_cvt_pk_bf16_f32 v34, v42, v40
	s_waitcnt lgkmcnt(4)
	v_cvt_pk_bf16_f32 v35, v44, v46
	s_waitcnt lgkmcnt(2)
	v_cvt_pk_bf16_f32 v36, v48, v50
	s_waitcnt lgkmcnt(0)
	v_cvt_pk_bf16_f32 v37, v52, v54
	v_lshl_add_u64 v[56:57], v[38:39], 0, v[56:57]
	v_add_u32_e32 v40, s0, v79
	global_store_dwordx4 v[56:57], v[34:37], off
	s_nop 1
	v_cvt_pk_bf16_f32 v34, v43, v41
	v_ashrrev_i32_e32 v41, 31, v40
	v_lshlrev_b64 v[40:41], 11, v[40:41]
	v_cvt_pk_bf16_f32 v35, v45, v47
	v_cvt_pk_bf16_f32 v36, v49, v51
	v_cvt_pk_bf16_f32 v37, v53, v55
	v_lshl_add_u64 v[38:39], v[38:39], 0, v[40:41]
	global_store_dwordx4 v[38:39], v[34:37], off
	s_waitcnt lgkmcnt(0)

; template <bool F8 = false>
; __device__ __forceinline__ void p0_transpose_item(const float* W, int K, int N, bf16_t* WT, int k0, int n0, int drow0, const float* gs, LAS float* scr, int lane) {
;     ...
;     for (int i = 0; i < 32; ++i) wv[i] = W[(size_t)(k0 + 2 * i + (lane >> 5)) * N + n0 + (lane & 31)];
;     if (gs) {
; #pragma unroll
;         for (int i = 0; i < 32; ++i) wv[i] *= gs[k0 + 2 * i + (lane >> 5)]; }
; #pragma unroll
;     for (int i = 0; i < 32; ++i) scr[(2 * i + (lane >> 5)) * 33 + (lane & 31)] = wv[i];
;     asm volatile("s_waitcnt lgkmcnt(0)" ::: "memory");
; template <int PART>
; __device__ __forceinline__ void phase0(const Ptrs& P, LAS float* scr, int gw, int NGW, int lane) {
;     ...
;         if (r < I_IN) { const int nblk = NIN / 32, kb = r / nblk, nb = r % nblk, n0 = 32 * nb, sec = n0 >> 10;
;             if (sec < 5) p0_transpose_item(P.w_in, DM, NIN, (bf16_t*)(ws + WS_WIN), 64 * kb, n0, n0, nullptr, scr, lane);
;             else p0_transpose_item<true>(P.w_in, DM, NIN, (bf16_t*)(ws + WS_WG8), 64 * kb, n0, n0 - 5120, nullptr, scr, lane);
.LBB0_443:
	s_andn2_b64 vcc, exec, s[0:1]
	s_cbranch_vccnz .LBB0_412
	s_add_i32 s0, s24, 0xe00
	s_mul_hi_i32 s1, s0, 0x92492493
	s_add_i32 s1, s1, s0
	s_lshr_b32 s2, s1, 31
	s_ashr_i32 s1, s1, 7
	s_add_i32 s1, s1, s2
	s_mul_i32 s2, s1, 0xe0
	s_sub_i32 s2, s0, s2
	s_lshl_b32 s4, s1, 6
	s_lshl_b32 s0, s2, 5
	v_add_u32_e32 v66, s4, v70
	s_cmpk_gt_i32 s2, 0x9f
	s_mov_b64 s[6:7], -1
	v_add_u32_e32 v65, 2, v66
	v_add_u32_e32 v64, 4, v66
	v_add_u32_e32 v63, 6, v66
	v_add_u32_e32 v62, 8, v66
	v_add_u32_e32 v61, 10, v66
	v_add_u32_e32 v60, 12, v66
	v_add_u32_e32 v59, 14, v66
	v_add_u32_e32 v58, 16, v66
	v_add_u32_e32 v57, 18, v66
	v_add_u32_e32 v56, 20, v66
	v_add_u32_e32 v55, 22, v66
	v_add_u32_e32 v54, 24, v66
	v_add_u32_e32 v53, 26, v66
	v_add_u32_e32 v52, 28, v66
	v_add_u32_e32 v51, 30, v66
	v_add_u32_e32 v50, 32, v66
	v_add_u32_e32 v49, 34, v66
	v_add_u32_e32 v48, 36, v66
	v_add_u32_e32 v47, 38, v66
	v_add_u32_e32 v46, 40, v66
	v_add_u32_e32 v45, 42, v66
	v_add_u32_e32 v44, 44, v66
	v_add_u32_e32 v43, 46, v66
	v_add_u32_e32 v42, 48, v66
	v_add_u32_e32 v41, 50, v66
	v_add_u32_e32 v40, 52, v66
	v_add_u32_e32 v39, 54, v66
	v_add_u32_e32 v38, 56, v66
	v_add_u32_e32 v37, 58, v66
	v_add_u32_e32 v36, 60, v66
	v_add_u32_e32 v35, 62, v66
	v_add_u32_e32 v34, 0x1c00, v71
	s_cbranch_scc0 .LBB0_446
	s_mov_b32 s1, s69
	v_lshl_add_u64 v[68:69], s[0:1], 2, v[32:33]
	v_mad_i64_i32 v[86:87], s[2:3], v66, s29, v[68:69]
	global_load_dword v67, v[86:87], off nt
	v_mad_i64_i32 v[86:87], s[2:3], v65, s29, v[68:69]
	global_load_dword v88, v[86:87], off nt
	v_mad_i64_i32 v[86:87], s[2:3], v64, s29, v[68:69]
	global_load_dword v89, v[86:87], off nt
	v_mad_i64_i32 v[86:87], s[2:3], v63, s29, v[68:69]
	global_load_dword v90, v[86:87], off nt
	v_mad_i64_i32 v[86:87], s[2:3], v62, s29, v[68:69]
	global_load_dword v91, v[86:87], off nt
	v_mad_i64_i32 v[86:87], s[2:3], v61, s29, v[68:69]
	global_load_dword v92, v[86:87], off nt
	v_mad_i64_i32 v[86:87], s[2:3], v60, s29, v[68:69]
	global_load_dword v93, v[86:87], off nt
	v_mad_i64_i32 v[86:87], s[2:3], v59, s29, v[68:69]
	global_load_dword v94, v[86:87], off nt
	v_mad_i64_i32 v[86:87], s[2:3], v58, s29, v[68:69]
	global_load_dword v95, v[86:87], off nt
	v_mad_i64_i32 v[86:87], s[2:3], v57, s29, v[68:69]
	global_load_dword v96, v[86:87], off nt
	v_mad_i64_i32 v[86:87], s[2:3], v56, s29, v[68:69]
	global_load_dword v97, v[86:87], off nt
	v_mad_i64_i32 v[86:87], s[2:3], v55, s29, v[68:69]
	global_load_dword v98, v[86:87], off nt
	v_mad_i64_i32 v[86:87], s[2:3], v54, s29, v[68:69]
	global_load_dword v99, v[86:87], off nt
	v_mad_i64_i32 v[86:87], s[2:3], v53, s29, v[68:69]
	global_load_dword v100, v[86:87], off nt
	v_mad_i64_i32 v[86:87], s[2:3], v52, s29, v[68:69]
	global_load_dword v101, v[86:87], off nt
	v_mad_i64_i32 v[86:87], s[2:3], v51, s29, v[68:69]
	global_load_dword v102, v[86:87], off nt
	v_mad_i64_i32 v[86:87], s[2:3], v50, s29, v[68:69]
	global_load_dword v103, v[86:87], off nt
	v_mad_i64_i32 v[86:87], s[2:3], v49, s29, v[68:69]
	global_load_dword v104, v[86:87], off nt
	v_mad_i64_i32 v[86:87], s[2:3], v48, s29, v[68:69]
	global_load_dword v105, v[86:87], off nt
	v_mad_i64_i32 v[86:87], s[2:3], v47, s29, v[68:69]
	global_load_dword v106, v[86:87], off nt
	v_mad_i64_i32 v[86:87], s[2:3], v46, s29, v[68:69]
	global_load_dword v107, v[86:87], off nt
	v_mad_i64_i32 v[86:87], s[2:3], v45, s29, v[68:69]
	global_load_dword v108, v[86:87], off nt
	v_mad_i64_i32 v[86:87], s[2:3], v44, s29, v[68:69]
	global_load_dword v109, v[86:87], off nt
	v_mad_i64_i32 v[86:87], s[2:3], v43, s29, v[68:69]
	global_load_dword v110, v[86:87], off nt
	v_mad_i64_i32 v[86:87], s[2:3], v42, s29, v[68:69]
	global_load_dword v111, v[86:87], off nt
	v_mad_i64_i32 v[86:87], s[2:3], v41, s29, v[68:69]
	global_load_dword v112, v[86:87], off nt
	v_mad_i64_i32 v[86:87], s[2:3], v40, s29, v[68:69]
	global_load_dword v113, v[86:87], off nt
	v_mad_i64_i32 v[86:87], s[2:3], v39, s29, v[68:69]
	global_load_dword v114, v[86:87], off nt
	v_mad_i64_i32 v[86:87], s[2:3], v38, s29, v[68:69]
	global_load_dword v115, v[86:87], off nt
	v_mad_i64_i32 v[86:87], s[2:3], v37, s29, v[68:69]
	global_load_dword v116, v[86:87], off nt
	v_mad_i64_i32 v[86:87], s[2:3], v36, s29, v[68:69]
	v_mad_i64_i32 v[68:69], s[2:3], v35, s29, v[68:69]
	global_load_dword v86, v[86:87], off nt
	s_add_i32 s1, s0, 0xffffec00
	global_load_dword v68, v[68:69], off nt
	s_waitcnt vmcnt(0)
	ds_write2_b32 v71, v67, v88 offset1:66
	ds_write2_b32 v71, v89, v90 offset0:132 offset1:198
	ds_write2_b32 v72, v91, v92 offset0:8 offset1:74
	ds_write2_b32 v72, v93, v94 offset0:140 offset1:206
	ds_write2_b32 v80, v95, v96 offset0:16 offset1:82
	ds_write2_b32 v80, v97, v98 offset0:148 offset1:214
	ds_write2_b32 v82, v99, v100 offset0:24 offset1:90
	ds_write2_b32 v82, v101, v102 offset0:156 offset1:222
	ds_write2_b32 v83, v103, v104 offset0:32 offset1:98
	ds_write2_b32 v83, v105, v106 offset0:164 offset1:230
	ds_write2_b32 v84, v107, v108 offset0:40 offset1:106
	ds_write2_b32 v84, v109, v110 offset0:172 offset1:238
	ds_write2_b32 v85, v111, v112 offset0:48 offset1:114
	ds_write2_b32 v85, v113, v114 offset0:180 offset1:246
	ds_write2_b32 v34, v115, v116 offset0:56 offset1:122
	ds_write2_b32 v34, v86, v68 offset0:188 offset1:254
	s_waitcnt lgkmcnt(0)
	ds_read2_b32 v[68:69], v76 offset1:8
	ds_read2_b32 v[86:87], v76 offset0:33 offset1:41
	ds_read2_b32 v[88:89], v76 offset0:66 offset1:74
	ds_read2_b32 v[92:93], v76 offset0:99 offset1:107
	ds_read2_b32 v[94:95], v76 offset0:132 offset1:140
	ds_read2_b32 v[96:97], v76 offset0:165 offset1:173
	v_mov_b32_e32 v98, v73
	s_waitcnt lgkmcnt(5)
; #define LAS __attribute__((address_space(3)))
; __device__ __forceinline__ unsigned pk_fp8x4(float a, float b, float c, float d) { int w = 0; w = __builtin_amdgcn_cvt_pk_fp8_f32(a, b, w, false); w = __builtin_amdgcn_cvt_pk_fp8_f32(c, d, w, true); return (unsigned)w; }
; template <bool F8 = false>
; __device__ __forceinline__ void p0_transpose_item(const float* W, int K, int N, bf16_t* WT, int k0, int n0, int drow0, const float* gs, LAS float* scr, int lane) {
;     ...
;     for (int j = 0; j < 4; ++j) { const int n = (lane >> 3) + 8 * j; const LAS float* s = scr + (8 * c) * 33 + n;
;         if (F8) { u32x2 o8; o8.x = pk_fp8x4(32.f * s[0 * 33], 32.f * s[1 * 33], 32.f * s[2 * 33], 32.f * s[3 * 33]); o8.y = pk_fp8x4(32.f * s[4 * 33], 32.f * s[5 * 33], 32.f * s[6 * 33], 32.f * s[7 * 33]);
;             *(u32x2*)((unsigned char*)WT + (size_t)(drow0 + n) * K + k0 + 8 * c) = o8; }
	v_mul_f32_e32 v67, 0x42000000, v68
	s_waitcnt lgkmcnt(4)
	v_mul_f32_e32 v68, 0x42000000, v86
	ds_read2_b32 v[100:101], v76 offset0:198 offset1:206
	ds_read2_b32 v[102:103], v76 offset0:231 offset1:239
	v_cvt_pk_fp8_f32 v98, v67, v68
	s_waitcnt lgkmcnt(3)
	v_mul_f32_e32 v67, 0x42000000, v94
	s_waitcnt lgkmcnt(2)
	v_mul_f32_e32 v68, 0x42000000, v96
	v_mov_b32_e32 v99, v73
	v_cvt_pk_fp8_f32 v99, v67, v68
	s_waitcnt lgkmcnt(1)
	v_mul_f32_e32 v67, 0x42000000, v100
	s_waitcnt lgkmcnt(0)
	v_mul_f32_e32 v68, 0x42000000, v102
	v_mul_f32_e32 v86, 0x42000000, v88
	v_mul_f32_e32 v88, 0x42000000, v92
	v_cvt_pk_fp8_f32 v99, v67, v68 op_sel:[0,0,1]
	v_mul_f32_e32 v67, 0x42000000, v69
	v_mul_f32_e32 v69, 0x42000000, v87
	v_mov_b32_e32 v68, v73
	v_cvt_pk_fp8_f32 v98, v86, v88 op_sel:[0,0,1]
	v_cvt_pk_fp8_f32 v68, v67, v69
	v_mul_f32_e32 v67, 0x42000000, v95
	v_mul_f32_e32 v88, 0x42000000, v97
	v_mov_b32_e32 v69, v73
	v_cvt_pk_fp8_f32 v69, v67, v88
	v_mul_f32_e32 v86, 0x42000000, v89
	v_mul_f32_e32 v87, 0x42000000, v93
	v_add_u32_e32 v104, s1, v75
	v_cvt_pk_fp8_f32 v68, v86, v87 op_sel:[0,0,1]
	v_mul_f32_e32 v67, 0x42000000, v101
	v_mul_f32_e32 v86, 0x42000000, v103
	s_ashr_i32 s5, s4, 31
	v_ashrrev_i32_e32 v105, 31, v104
	v_cvt_pk_fp8_f32 v69, v67, v86 op_sel:[0,0,1]
	v_add_u32_e32 v86, s1, v77
	v_lshl_add_u64 v[90:91], v[14:15], 0, s[4:5]
	v_lshlrev_b64 v[104:105], 10, v[104:105]
	v_ashrrev_i32_e32 v87, 31, v86
	v_lshl_add_u64 v[104:105], v[90:91], 0, v[104:105]
	v_lshlrev_b64 v[86:87], 10, v[86:87]
	global_store_dwordx2 v[104:105], v[98:99], off
	v_lshl_add_u64 v[86:87], v[90:91], 0, v[86:87]
	ds_read2_b32 v[88:89], v76 offset0:16 offset1:24
	ds_read2_b32 v[92:93], v76 offset0:49 offset1:57
	ds_read2_b32 v[94:95], v76 offset0:82 offset1:90
	global_store_dwordx2 v[86:87], v[68:69], off
	ds_read2_b32 v[68:69], v76 offset0:115 offset1:123
	ds_read2_b32 v[86:87], v76 offset0:148 offset1:156
	ds_read2_b32 v[96:97], v76 offset0:181 offset1:189
	s_waitcnt lgkmcnt(5)
	v_mul_f32_e32 v67, 0x42000000, v88
	s_waitcnt lgkmcnt(4)
	v_mul_f32_e32 v88, 0x42000000, v92
	v_mov_b32_e32 v98, v73
	ds_read2_b32 v[100:101], v76 offset0:214 offset1:222
	ds_read2_b32 v[102:103], v76 offset0:247 offset1:255
	v_cvt_pk_fp8_f32 v98, v67, v88
	s_waitcnt lgkmcnt(3)
	v_mul_f32_e32 v67, 0x42000000, v86
	s_waitcnt lgkmcnt(2)
	v_mul_f32_e32 v86, 0x42000000, v96
	v_mov_b32_e32 v99, v73
	v_cvt_pk_fp8_f32 v99, v67, v86
	v_mul_f32_e32 v92, 0x42000000, v94
	v_mul_f32_e32 v68, 0x42000000, v68
	v_cvt_pk_fp8_f32 v98, v92, v68 op_sel:[0,0,1]
	s_waitcnt lgkmcnt(1)
	v_mul_f32_e32 v67, 0x42000000, v100
	s_waitcnt lgkmcnt(0)
	v_mul_f32_e32 v68, 0x42000000, v102
	v_cvt_pk_fp8_f32 v99, v67, v68 op_sel:[0,0,1]
	v_mul_f32_e32 v67, 0x42000000, v89
	v_mul_f32_e32 v86, 0x42000000, v93
	v_mov_b32_e32 v68, v73
	v_mul_f32_e32 v89, 0x42000000, v69
	v_cvt_pk_fp8_f32 v68, v67, v86
	v_mul_f32_e32 v67, 0x42000000, v87
	v_mul_f32_e32 v86, 0x42000000, v97
	v_mov_b32_e32 v69, v73
	v_cvt_pk_fp8_f32 v69, v67, v86
	v_mul_f32_e32 v88, 0x42000000, v95
	v_mul_f32_e32 v67, 0x42000000, v101
	v_mul_f32_e32 v86, 0x42000000, v103
	v_add_u32_e32 v104, s1, v78
	v_cvt_pk_fp8_f32 v68, v88, v89 op_sel:[0,0,1]
	v_cvt_pk_fp8_f32 v69, v67, v86 op_sel:[0,0,1]
	v_add_u32_e32 v86, s1, v79
	v_ashrrev_i32_e32 v105, 31, v104
	v_ashrrev_i32_e32 v87, 31, v86
	v_lshlrev_b64 v[104:105], 10, v[104:105]
	v_lshlrev_b64 v[86:87], 10, v[86:87]
	v_lshl_add_u64 v[104:105], v[90:91], 0, v[104:105]
	v_lshl_add_u64 v[86:87], v[90:91], 0, v[86:87]
	global_store_dwordx2 v[104:105], v[98:99], off
	global_store_dwordx2 v[86:87], v[68:69], off
	s_waitcnt lgkmcnt(0)
	s_mov_b64 s[6:7], 0
; #define LAS __attribute__((address_space(3)))
; __device__ __forceinline__ unsigned cvt_pk(float lo, float hi) { f32x2_t v = {lo, hi}; bf16x2_t b = __builtin_convertvector(v, bf16x2_t); return __builtin_bit_cast(unsigned, b); }
; __device__ __forceinline__ unsigned pk_fp8x4(float a, float b, float c, float d) { int w = 0; w = __builtin_amdgcn_cvt_pk_fp8_f32(a, b, w, false); w = __builtin_amdgcn_cvt_pk_fp8_f32(c, d, w, true); return (unsigned)w; }
; template <bool F8 = false>
; __device__ __forceinline__ void p0_transpose_item(const float* W, int K, int N, bf16_t* WT, int k0, int n0, int drow0, const float* gs, LAS float* scr, int lane) {
;     ...
;     for (int i = 0; i < 32; ++i) wv[i] = W[(size_t)(k0 + 2 * i + (lane >> 5)) * N + n0 + (lane & 31)];
;     if (gs) {
; #pragma unroll
;         for (int i = 0; i < 32; ++i) wv[i] *= gs[k0 + 2 * i + (lane >> 5)]; }
; #pragma unroll
;     for (int i = 0; i < 32; ++i) scr[(2 * i + (lane >> 5)) * 33 + (lane & 31)] = wv[i];
;     asm volatile("s_waitcnt lgkmcnt(0)" ::: "memory");
;     const int c = lane & 7;
; #pragma unroll
;     for (int j = 0; j < 4; ++j) { const int n = (lane >> 3) + 8 * j; const LAS float* s = scr + (8 * c) * 33 + n;
;         if (F8) { u32x2 o8; o8.x = pk_fp8x4(32.f * s[0 * 33], 32.f * s[1 * 33], 32.f * s[2 * 33], 32.f * s[3 * 33]); o8.y = pk_fp8x4(32.f * s[4 * 33], 32.f * s[5 * 33], 32.f * s[6 * 33], 32.f * s[7 * 33]);
;             *(u32x2*)((unsigned char*)WT + (size_t)(drow0 + n) * K + k0 + 8 * c) = o8; }
;         else { u32x4 o; o.x = cvt_pk(s[0 * 33], s[1 * 33]); o.y = cvt_pk(s[2 * 33], s[3 * 33]); o.z = cvt_pk(s[4 * 33], s[5 * 33]); o.w = cvt_pk(s[6 * 33], s[7 * 33]);
;             *(u32x4*)(WT + (size_t)(drow0 + n) * K + k0 + 8 * c) = o; } }
; template <int PART>
; __device__ __forceinline__ void phase0(const Ptrs& P, LAS float* scr, int gw, int NGW, int lane) {
;     ...
;             if (sec < 5) p0_transpose_item(P.w_in, DM, NIN, (bf16_t*)(ws + WS_WIN), 64 * kb, n0, n0, nullptr, scr, lane);
.LBB0_446:
	s_andn2_b64 vcc, exec, s[6:7]
	s_cbranch_vccnz .LBB0_412
	s_ashr_i32 s1, s0, 31
	v_lshl_add_u64 v[68:69], s[0:1], 2, v[32:33]
	v_mad_i64_i32 v[66:67], s[2:3], v66, s29, v[68:69]
	global_load_dword v86, v[66:67], off nt
	v_mad_i64_i32 v[66:67], s[2:3], v65, s29, v[68:69]
	v_mad_i64_i32 v[64:65], s[2:3], v64, s29, v[68:69]
	global_load_dword v66, v[66:67], off nt
	s_ashr_i32 s5, s4, 31
	global_load_dword v67, v[64:65], off nt
	v_mad_i64_i32 v[64:65], s[2:3], v63, s29, v[68:69]
	v_mad_i64_i32 v[62:63], s[2:3], v62, s29, v[68:69]
	global_load_dword v64, v[64:65], off nt
	s_nop 0
	global_load_dword v65, v[62:63], off nt
	v_mad_i64_i32 v[62:63], s[2:3], v61, s29, v[68:69]
	v_mad_i64_i32 v[60:61], s[2:3], v60, s29, v[68:69]
	global_load_dword v62, v[62:63], off nt
	s_nop 0
	global_load_dword v63, v[60:61], off nt
	v_mad_i64_i32 v[60:61], s[2:3], v59, s29, v[68:69]
	v_mad_i64_i32 v[58:59], s[2:3], v58, s29, v[68:69]
	global_load_dword v60, v[60:61], off nt
	s_nop 0
	global_load_dword v61, v[58:59], off nt
	v_mad_i64_i32 v[58:59], s[2:3], v57, s29, v[68:69]
	v_mad_i64_i32 v[56:57], s[2:3], v56, s29, v[68:69]
	global_load_dword v58, v[58:59], off nt
	s_nop 0
	global_load_dword v59, v[56:57], off nt
	v_mad_i64_i32 v[56:57], s[2:3], v55, s29, v[68:69]
	v_mad_i64_i32 v[54:55], s[2:3], v54, s29, v[68:69]
	global_load_dword v56, v[56:57], off nt
	s_nop 0
	global_load_dword v57, v[54:55], off nt
	v_mad_i64_i32 v[54:55], s[2:3], v53, s29, v[68:69]
	v_mad_i64_i32 v[52:53], s[2:3], v52, s29, v[68:69]
	global_load_dword v54, v[54:55], off nt
	s_nop 0
	global_load_dword v55, v[52:53], off nt
	v_mad_i64_i32 v[52:53], s[2:3], v51, s29, v[68:69]
	v_mad_i64_i32 v[50:51], s[2:3], v50, s29, v[68:69]
	global_load_dword v52, v[52:53], off nt
	s_nop 0
	global_load_dword v53, v[50:51], off nt
	v_mad_i64_i32 v[50:51], s[2:3], v49, s29, v[68:69]
	v_mad_i64_i32 v[48:49], s[2:3], v48, s29, v[68:69]
	global_load_dword v50, v[50:51], off nt
	s_nop 0
	global_load_dword v51, v[48:49], off nt
	v_mad_i64_i32 v[48:49], s[2:3], v47, s29, v[68:69]
	v_mad_i64_i32 v[46:47], s[2:3], v46, s29, v[68:69]
	global_load_dword v48, v[48:49], off nt
	s_nop 0
	global_load_dword v49, v[46:47], off nt
	v_mad_i64_i32 v[46:47], s[2:3], v45, s29, v[68:69]
	v_mad_i64_i32 v[44:45], s[2:3], v44, s29, v[68:69]
	global_load_dword v46, v[46:47], off nt
	s_nop 0
	global_load_dword v47, v[44:45], off nt
	v_mad_i64_i32 v[44:45], s[2:3], v43, s29, v[68:69]
	v_mad_i64_i32 v[42:43], s[2:3], v42, s29, v[68:69]
	global_load_dword v44, v[44:45], off nt
	s_nop 0
	global_load_dword v45, v[42:43], off nt
	v_mad_i64_i32 v[42:43], s[2:3], v41, s29, v[68:69]
	v_mad_i64_i32 v[40:41], s[2:3], v40, s29, v[68:69]
	global_load_dword v42, v[42:43], off nt
	s_nop 0
	global_load_dword v43, v[40:41], off nt
	v_mad_i64_i32 v[40:41], s[2:3], v39, s29, v[68:69]
	v_mad_i64_i32 v[38:39], s[2:3], v38, s29, v[68:69]
	global_load_dword v40, v[40:41], off nt
	s_nop 0
	global_load_dword v41, v[38:39], off nt
	v_mad_i64_i32 v[38:39], s[2:3], v37, s29, v[68:69]
	v_mad_i64_i32 v[36:37], s[2:3], v36, s29, v[68:69]
	global_load_dword v38, v[38:39], off nt
	s_nop 0
	global_load_dword v39, v[36:37], off nt
	v_mad_i64_i32 v[36:37], s[2:3], v35, s29, v[68:69]
	global_load_dword v35, v[36:37], off nt
	s_waitcnt vmcnt(0)
	ds_write2_b32 v71, v86, v66 offset1:66
	ds_write2_b32 v71, v67, v64 offset0:132 offset1:198
	ds_write2_b32 v72, v65, v62 offset0:8 offset1:74
	ds_write2_b32 v72, v63, v60 offset0:140 offset1:206
	ds_write2_b32 v80, v61, v58 offset0:16 offset1:82
	ds_write2_b32 v80, v59, v56 offset0:148 offset1:214
	ds_write2_b32 v82, v57, v54 offset0:24 offset1:90
	ds_write2_b32 v82, v55, v52 offset0:156 offset1:222
	ds_write2_b32 v83, v53, v50 offset0:32 offset1:98
	ds_write2_b32 v83, v51, v48 offset0:164 offset1:230
	ds_write2_b32 v84, v49, v46 offset0:40 offset1:106
	ds_write2_b32 v84, v47, v44 offset0:172 offset1:238
	ds_write2_b32 v85, v45, v42 offset0:48 offset1:114
	ds_write2_b32 v85, v43, v40 offset0:180 offset1:246
	ds_write2_b32 v34, v41, v38 offset0:56 offset1:122
	ds_write2_b32 v34, v39, v35 offset0:188 offset1:254
	s_waitcnt lgkmcnt(0)
	ds_read2_b32 v[40:41], v76 offset0:33 offset1:41
	ds_read2_b32 v[42:43], v76 offset1:8
	ds_read2_b32 v[44:45], v76 offset0:66 offset1:74
	ds_read2_b32 v[46:47], v76 offset0:99 offset1:107
	ds_read2_b32 v[48:49], v76 offset0:132 offset1:140
	ds_read2_b32 v[50:51], v76 offset0:165 offset1:173
	ds_read2_b32 v[52:53], v76 offset0:198 offset1:206
	ds_read2_b32 v[54:55], v76 offset0:231 offset1:239
	v_add_u32_e32 v56, s0, v75
	v_ashrrev_i32_e32 v57, 31, v56
	v_lshl_add_u64 v[38:39], s[4:5], 1, v[16:17]
	v_lshlrev_b64 v[56:57], 11, v[56:57]
	s_waitcnt lgkmcnt(6)
	v_cvt_pk_bf16_f32 v34, v42, v40
	s_waitcnt lgkmcnt(4)
	v_cvt_pk_bf16_f32 v35, v44, v46
	s_waitcnt lgkmcnt(2)
	v_cvt_pk_bf16_f32 v36, v48, v50
	s_waitcnt lgkmcnt(0)
	v_cvt_pk_bf16_f32 v37, v52, v54
	v_lshl_add_u64 v[56:57], v[38:39], 0, v[56:57]
	v_add_u32_e32 v40, s0, v77
	global_store_dwordx4 v[56:57], v[34:37], off
	v_add_u32_e32 v56, s0, v78
	v_ashrrev_i32_e32 v57, 31, v56
	v_cvt_pk_bf16_f32 v34, v43, v41
	v_ashrrev_i32_e32 v41, 31, v40
	v_lshlrev_b64 v[40:41], 11, v[40:41]
	v_cvt_pk_bf16_f32 v35, v45, v47
	v_cvt_pk_bf16_f32 v36, v49, v51
	v_cvt_pk_bf16_f32 v37, v53, v55
	v_lshl_add_u64 v[40:41], v[38:39], 0, v[40:41]
	global_store_dwordx4 v[40:41], v[34:37], off
	ds_read2_b32 v[40:41], v76 offset0:49 offset1:57
	ds_read2_b32 v[42:43], v76 offset0:16 offset1:24
	ds_read2_b32 v[44:45], v76 offset0:82 offset1:90
	ds_read2_b32 v[46:47], v76 offset0:115 offset1:123
	ds_read2_b32 v[48:49], v76 offset0:148 offset1:156
	ds_read2_b32 v[50:51], v76 offset0:181 offset1:189
	ds_read2_b32 v[52:53], v76 offset0:214 offset1:222
	ds_read2_b32 v[54:55], v76 offset0:247 offset1:255
	v_lshlrev_b64 v[56:57], 11, v[56:57]
	s_waitcnt lgkmcnt(6)
	v_cvt_pk_bf16_f32 v34, v42, v40
	s_waitcnt lgkmcnt(4)
	v_cvt_pk_bf16_f32 v35, v44, v46
	s_waitcnt lgkmcnt(2)
	v_cvt_pk_bf16_f32 v36, v48, v50
	s_waitcnt lgkmcnt(0)
	v_cvt_pk_bf16_f32 v37, v52, v54
	v_lshl_add_u64 v[56:57], v[38:39], 0, v[56:57]
	v_add_u32_e32 v40, s0, v79
	global_store_dwordx4 v[56:57], v[34:37], off
	s_nop 1
	v_cvt_pk_bf16_f32 v34, v43, v41
	v_ashrrev_i32_e32 v41, 31, v40
	v_lshlrev_b64 v[40:41], 11, v[40:41]
	v_cvt_pk_bf16_f32 v35, v45, v47
	v_cvt_pk_bf16_f32 v36, v49, v51
	v_cvt_pk_bf16_f32 v37, v53, v55
	v_lshl_add_u64 v[38:39], v[38:39], 0, v[40:41]
	global_store_dwordx4 v[38:39], v[34:37], off
	s_waitcnt lgkmcnt(0)
	s_branch .LBB0_412

; __device__ __forceinline__ u32x4 pack8(f32x4 a, f32x4 b) { u32x4 w; w.x = cvt_pk(a[0], a[1]); w.y = cvt_pk(a[2], a[3]); w.z = cvt_pk(b[0], b[1]); w.w = cvt_pk(b[2], b[3]); return w; }
; template <int PART>
; __device__ __forceinline__ void phase0(const Ptrs& P, LAS float* scr, int gw, int NGW, int lane) {
;     ...
;     if (PART == 1) { bf16_t* PB = (bf16_t*)(ws + WS_PB); const int ngrp = MT * PLE / 8;
; #pragma unroll 4
;         for (int gidx = gw * 64 + lane; gidx < ngrp; gidx += NGW * 64) { const f32x4 a = *(const f32x4*)(P.p + (size_t)gidx * 8), b = *(const f32x4*)(P.p + (size_t)gidx * 8 + 4); *(u32x4*)(PB + (size_t)gidx * 8) = pack8(a, b); } }
.LBB0_451:
	global_load_dwordx4 v[8:11], v[4:5], off offset:-16 nt
	global_load_dwordx4 v[12:15], v[4:5], off nt
	v_add_u32_e32 v7, -1, v7
	v_cmp_eq_u32_e64 s[0:1], 0, v7
	v_add_u32_e32 v0, s62, v0
	v_lshl_add_u64 v[4:5], v[4:5], 0, s[44:45]
	s_or_b64 s[36:37], s[0:1], s[36:37]
	s_waitcnt vmcnt(0)
	v_cvt_pk_bf16_f32 v8, v8, v9
	v_cvt_pk_bf16_f32 v9, v10, v11
	v_cvt_pk_bf16_f32 v10, v12, v13
	v_cvt_pk_bf16_f32 v11, v14, v15
	global_store_dwordx4 v[2:3], v[8:11], off
	v_lshl_add_u64 v[2:3], v[2:3], 0, s[2:3]
	s_andn2_b64 exec, exec, s[36:37]
	s_cbranch_execnz .LBB0_451
	s_or_b64 exec, exec, s[36:37]

; __device__ __forceinline__ u32x4 pack8(f32x4 a, f32x4 b) { u32x4 w; w.x = cvt_pk(a[0], a[1]); w.y = cvt_pk(a[2], a[3]); w.z = cvt_pk(b[0], b[1]); w.w = cvt_pk(b[2], b[3]); return w; }
; template <int PART>
; __device__ __forceinline__ void phase0(const Ptrs& P, LAS float* scr, int gw, int NGW, int lane) {
;     ...
;     if (PART == 1) { bf16_t* PB = (bf16_t*)(ws + WS_PB); const int ngrp = MT * PLE / 8;
; #pragma unroll 4
;         for (int gidx = gw * 64 + lane; gidx < ngrp; gidx += NGW * 64) { const f32x4 a = *(const f32x4*)(P.p + (size_t)gidx * 8), b = *(const f32x4*)(P.p + (size_t)gidx * 8 + 4); *(u32x4*)(PB + (size_t)gidx * 8) = pack8(a, b); } }
.LBB0_455:
	v_ashrrev_i32_e32 v1, 31, v0
	v_lshlrev_b64 v[2:3], 5, v[0:1]
	v_lshl_add_u64 v[6:7], s[78:79], 0, v[2:3]
	global_load_dwordx4 v[2:5], v[6:7], off offset:16 nt
	s_nop 0
	global_load_dwordx4 v[6:9], v[6:7], off nt
	v_add_u32_e32 v10, s62, v0
	v_ashrrev_i32_e32 v11, 31, v10
	v_add_u32_e32 v12, s8, v0
	v_ashrrev_i32_e32 v13, 31, v12
	s_mul_i32 s2, s6, 0x600
	s_waitcnt vmcnt(0)
	v_cvt_pk_bf16_f32 v6, v6, v7
	v_cvt_pk_bf16_f32 v7, v8, v9
	v_cvt_pk_bf16_f32 v8, v2, v3
	v_cvt_pk_bf16_f32 v9, v4, v5
	v_lshl_add_u64 v[2:3], v[0:1], 4, s[60:61]
	global_store_dwordx4 v[2:3], v[6:9], off
	v_lshlrev_b64 v[2:3], 5, v[10:11]
	s_nop 0
	v_lshl_add_u64 v[6:7], s[78:79], 0, v[2:3]
	global_load_dwordx4 v[2:5], v[6:7], off offset:16 nt
	s_nop 0
	global_load_dwordx4 v[6:9], v[6:7], off nt
	s_waitcnt vmcnt(0)
	v_cvt_pk_bf16_f32 v6, v6, v7
	v_cvt_pk_bf16_f32 v7, v8, v9
	v_cvt_pk_bf16_f32 v8, v2, v3
	v_cvt_pk_bf16_f32 v9, v4, v5
	v_lshl_add_u64 v[2:3], v[10:11], 4, s[60:61]
	global_store_dwordx4 v[2:3], v[6:9], off
	v_lshlrev_b64 v[2:3], 5, v[12:13]
	s_nop 0
	v_lshl_add_u64 v[6:7], s[78:79], 0, v[2:3]
	global_load_dwordx4 v[2:5], v[6:7], off offset:16 nt
	s_nop 0
	global_load_dwordx4 v[6:9], v[6:7], off nt
	s_waitcnt vmcnt(0)
	v_cvt_pk_bf16_f32 v6, v6, v7
	v_cvt_pk_bf16_f32 v7, v8, v9
	v_cvt_pk_bf16_f32 v8, v2, v3
	v_cvt_pk_bf16_f32 v9, v4, v5
	v_lshl_add_u64 v[2:3], v[12:13], 4, s[60:61]
	global_store_dwordx4 v[2:3], v[6:9], off
	s_nop 1
	v_add_u32_e32 v8, s2, v0
	v_ashrrev_i32_e32 v9, 31, v8
	v_lshlrev_b64 v[0:1], 5, v[8:9]
	v_lshl_add_u64 v[4:5], s[78:79], 0, v[0:1]
	global_load_dwordx4 v[0:3], v[4:5], off offset:16 nt
	s_nop 0
	global_load_dwordx4 v[4:7], v[4:5], off nt
	s_add_i32 s2, s62, s62
	s_add_i32 s2, s2, s62
	s_waitcnt vmcnt(0)
	v_cvt_pk_bf16_f32 v4, v4, v5
	v_cvt_pk_bf16_f32 v5, v6, v7
	v_cvt_pk_bf16_f32 v6, v0, v1
	v_cvt_pk_bf16_f32 v7, v2, v3
	v_lshl_add_u64 v[0:1], v[8:9], 4, s[60:61]
	global_store_dwordx4 v[0:1], v[4:7], off
	v_add_u32_e32 v0, s2, v10
	s_mov_b32 s2, 0x7ffff
	v_cmp_lt_i32_e32 vcc, s2, v0
	s_or_b64 s[0:1], vcc, s[0:1]
	s_andn2_b64 exec, exec, s[0:1]
	s_cbranch_execnz .LBB0_455
